# same accumulate-chain MFMA order but n-major snake (B fragment pair fixed across four chains)
# speedup vs baseline: 1.0139x; 1.0025x over previous
.LBB0_166:
	s_add_u32 s42, s2, 0x10000
	s_waitcnt lgkmcnt(0)
	s_addc_u32 s43, s3, 0
	s_add_u32 s52, s48, 0x10000
	s_addc_u32 s53, s49, 0
	s_barrier
	s_setprio 1
	s_waitcnt lgkmcnt(7)
	s_waitcnt lgkmcnt(0)
	v_mfma_f32_16x16x32_bf16 v[32:35], v[16:19], v[76:79], 0
	v_mfma_f32_16x16x32_bf16 v[32:35], v[20:23], v[84:87], v[32:35]
	v_mfma_f32_16x16x32_bf16 v[40:43], v[16:19], v[92:95], 0
	v_mfma_f32_16x16x32_bf16 v[40:43], v[20:23], v[96:99], v[40:43]
	v_mfma_f32_16x16x32_bf16 v[48:51], v[16:19], v[80:83], 0
	v_mfma_f32_16x16x32_bf16 v[48:51], v[20:23], v[88:91], v[48:51]
	v_mfma_f32_16x16x32_bf16 v[56:59], v[16:19], v[60:63], 0
	v_mfma_f32_16x16x32_bf16 v[56:59], v[20:23], v[72:75], v[56:59]
	v_mfma_f32_16x16x32_bf16 v[64:67], v[24:27], v[60:63], 0
	v_mfma_f32_16x16x32_bf16 v[64:67], v[28:31], v[72:75], v[64:67]
	v_mfma_f32_16x16x32_bf16 v[52:55], v[24:27], v[80:83], 0
	v_mfma_f32_16x16x32_bf16 v[52:55], v[28:31], v[88:91], v[52:55]
	v_mfma_f32_16x16x32_bf16 v[44:47], v[24:27], v[92:95], 0
	v_mfma_f32_16x16x32_bf16 v[44:47], v[28:31], v[96:99], v[44:47]
	v_mfma_f32_16x16x32_bf16 v[36:39], v[24:27], v[76:79], 0
	v_mfma_f32_16x16x32_bf16 v[36:39], v[28:31], v[84:87], v[36:39]
	s_setprio 0
	s_setprio 1
	v_mfma_f32_16x16x32_bf16 v[68:71], v[0:3], v[76:79], 0
	v_mfma_f32_16x16x32_bf16 v[76:79], v[8:11], v[76:79], 0
	v_mfma_f32_16x16x32_bf16 v[68:71], v[4:7], v[84:87], v[68:71]
	v_mfma_f32_16x16x32_bf16 v[76:79], v[12:15], v[84:87], v[76:79]
	v_mfma_f32_16x16x32_bf16 v[84:87], v[0:3], v[92:95], 0
	v_mfma_f32_16x16x32_bf16 v[92:95], v[8:11], v[92:95], 0
	v_mfma_f32_16x16x32_bf16 v[84:87], v[4:7], v[96:99], v[84:87]
	v_mfma_f32_16x16x32_bf16 v[92:95], v[12:15], v[96:99], v[92:95]
	v_mfma_f32_16x16x32_bf16 v[96:99], v[0:3], v[80:83], 0
	v_mfma_f32_16x16x32_bf16 v[80:83], v[8:11], v[80:83], 0
	v_mfma_f32_16x16x32_bf16 v[132:135], v[12:15], v[88:91], v[80:83]
	v_mfma_f32_16x16x32_bf16 v[80:83], v[0:3], v[60:63], 0
	v_mfma_f32_16x16x32_bf16 v[60:63], v[8:11], v[60:63], 0
	v_mfma_f32_16x16x32_bf16 v[128:131], v[4:7], v[88:91], v[96:99]
	v_mfma_f32_16x16x32_bf16 v[136:139], v[4:7], v[72:75], v[80:83]
	v_mfma_f32_16x16x32_bf16 v[140:143], v[12:15], v[72:75], v[60:63]
	s_setprio 0
	s_barrier
	ds_read_b128 v[104:107], v170 offset:16384
	ds_read_b128 v[108:111], v170 offset:17408
	ds_read_b128 v[96:99], v170 offset:18432
	ds_read_b128 v[100:103], v170 offset:19456
	ds_read_b128 v[80:83], v170 offset:20480
	ds_read_b128 v[88:91], v170 offset:21504
	ds_read_b128 v[60:63], v170 offset:22528
	ds_read_b128 v[72:75], v170 offset:23552
	s_mov_b32 m0, s45
	s_nop 0
	global_load_lds_dwordx4 v166, s[52:53]
	s_add_u32 s52, s48, 0x12000
	s_addc_u32 s53, s49, 0
	s_mov_b32 m0, s47
	s_nop 0
	global_load_lds_dwordx4 v166, s[52:53]
	s_add_u32 s52, s48, 0x14000
	s_addc_u32 s53, s49, 0
	s_mov_b32 m0, s58
	s_nop 0
	global_load_lds_dwordx4 v166, s[52:53]
	s_add_u32 s52, s48, 0x16000
	s_addc_u32 s53, s49, 0
	s_mov_b32 m0, s59
	s_nop 0
	global_load_lds_dwordx4 v166, s[52:53]
	s_nop 0
	s_mov_b32 m0, s57
	s_nop 0
	global_load_lds_dwordx4 v166, s[42:43]
	s_add_u32 s42, s2, 0x12000
	s_addc_u32 s43, s3, 0
	s_mov_b32 m0, s60
	s_nop 0
	global_load_lds_dwordx4 v166, s[42:43]
	s_and_b64 vcc, exec, s[40:41]
	s_cbranch_vccz .LBB0_177
	s_waitcnt vmcnt(16)
	s_cbranch_execnz .LBB0_169

.LBB0_170:
	ds_read_b128 v[128:131], v168
	ds_read_b128 v[132:135], v168 offset:1024
	ds_read_b128 v[136:139], v168 offset:2048
	ds_read_b128 v[140:143], v168 offset:3072
	ds_read_b128 v[152:155], v169
	ds_read_b128 v[156:159], v169 offset:1024
	ds_read_b128 v[160:163], v169 offset:2048
	ds_read_b128 v[172:175], v169 offset:3072
	s_add_u32 s2, s52, 0x10000
	s_addc_u32 s3, s53, 0
	s_cmp_eq_u32 s88, 60
	s_cselect_b32 s48, s82, s2
	s_cselect_b32 s49, s39, s3
	s_cselect_b32 s90, s83, s54
	s_cselect_b32 s91, s15, s55
	s_add_u32 s80, s48, 0x8000
	s_addc_u32 s81, s49, 0
	ds_read_b128 v[176:179], v170
	ds_read_b128 v[180:183], v170 offset:1024
	ds_read_b128 v[184:187], v170 offset:2048
	ds_read_b128 v[188:191], v170 offset:3072
	ds_read_b128 v[192:195], v170 offset:4096
	ds_read_b128 v[196:199], v170 offset:5120
	ds_read_b128 v[200:203], v170 offset:6144
	ds_read_b128 v[204:207], v170 offset:7168
	s_add_u32 s92, s52, 0xc000
	s_addc_u32 s93, s53, 0
	s_mov_b32 m0, s72
	s_nop 0
	global_load_lds_dwordx4 v166, s[92:93]
	s_add_u32 s52, s52, 0xe000
	s_addc_u32 s53, s53, 0
	s_mov_b32 m0, s75
	s_nop 0
	global_load_lds_dwordx4 v166, s[52:53]
	s_waitcnt vmcnt(8)
	s_waitcnt lgkmcnt(0)
	s_add_u32 s92, s90, 0x8000
	s_addc_u32 s93, s91, 0
	s_barrier
	s_setprio 1
	s_waitcnt lgkmcnt(7)
	s_waitcnt lgkmcnt(0)
	v_mfma_f32_16x16x32_bf16 v[112:115], v[128:131], v[176:179], v[112:115]
	v_mfma_f32_16x16x32_bf16 v[112:115], v[132:135], v[180:183], v[112:115]
	v_mfma_f32_16x16x32_bf16 v[96:99], v[128:131], v[184:187], v[96:99]
	v_mfma_f32_16x16x32_bf16 v[96:99], v[132:135], v[188:191], v[96:99]
	v_mfma_f32_16x16x32_bf16 v[80:83], v[128:131], v[192:195], v[80:83]
	v_mfma_f32_16x16x32_bf16 v[80:83], v[132:135], v[196:199], v[80:83]
	v_mfma_f32_16x16x32_bf16 v[60:63], v[128:131], v[200:203], v[60:63]
	v_mfma_f32_16x16x32_bf16 v[60:63], v[132:135], v[204:207], v[60:63]
	v_mfma_f32_16x16x32_bf16 v[72:75], v[136:139], v[200:203], v[72:75]
	v_mfma_f32_16x16x32_bf16 v[72:75], v[140:143], v[204:207], v[72:75]
	v_mfma_f32_16x16x32_bf16 v[88:91], v[136:139], v[192:195], v[88:91]
	v_mfma_f32_16x16x32_bf16 v[88:91], v[140:143], v[196:199], v[88:91]
	v_mfma_f32_16x16x32_bf16 v[104:107], v[136:139], v[184:187], v[104:107]
	v_mfma_f32_16x16x32_bf16 v[104:107], v[140:143], v[188:191], v[104:107]
	v_mfma_f32_16x16x32_bf16 v[120:123], v[136:139], v[176:179], v[120:123]
	v_mfma_f32_16x16x32_bf16 v[120:123], v[140:143], v[180:183], v[120:123]
	s_setprio 0
	s_setprio 1
	s_waitcnt lgkmcnt(0)
	v_mfma_f32_16x16x32_bf16 v[116:119], v[152:155], v[176:179], v[116:119]
	v_mfma_f32_16x16x32_bf16 v[116:119], v[156:159], v[180:183], v[116:119]
	v_mfma_f32_16x16x32_bf16 v[100:103], v[152:155], v[184:187], v[100:103]
	v_mfma_f32_16x16x32_bf16 v[100:103], v[156:159], v[188:191], v[100:103]
	v_mfma_f32_16x16x32_bf16 v[84:87], v[152:155], v[192:195], v[84:87]
	v_mfma_f32_16x16x32_bf16 v[84:87], v[156:159], v[196:199], v[84:87]
	v_mfma_f32_16x16x32_bf16 v[68:71], v[152:155], v[200:203], v[68:71]
	v_mfma_f32_16x16x32_bf16 v[68:71], v[156:159], v[204:207], v[68:71]
	v_mfma_f32_16x16x32_bf16 v[76:79], v[160:163], v[200:203], v[76:79]
	v_mfma_f32_16x16x32_bf16 v[76:79], v[172:175], v[204:207], v[76:79]
	v_mfma_f32_16x16x32_bf16 v[92:95], v[160:163], v[192:195], v[92:95]
	v_mfma_f32_16x16x32_bf16 v[92:95], v[172:175], v[196:199], v[92:95]
	v_mfma_f32_16x16x32_bf16 v[108:111], v[160:163], v[184:187], v[108:111]
	v_mfma_f32_16x16x32_bf16 v[108:111], v[172:175], v[188:191], v[108:111]
	v_mfma_f32_16x16x32_bf16 v[124:127], v[160:163], v[176:179], v[124:127]
	v_mfma_f32_16x16x32_bf16 v[124:127], v[172:175], v[180:183], v[124:127]
	s_setprio 0
	s_barrier
	s_add_u32 s52, s90, 0x2000
	ds_read_b128 v[176:179], v170 offset:16384
	ds_read_b128 v[180:183], v170 offset:17408
	ds_read_b128 v[184:187], v170 offset:18432
	ds_read_b128 v[188:191], v170 offset:19456
	ds_read_b128 v[192:195], v170 offset:20480
	ds_read_b128 v[196:199], v170 offset:21504
	ds_read_b128 v[200:203], v170 offset:22528
	ds_read_b128 v[204:207], v170 offset:23552
	s_mov_b32 m0, s45
	s_nop 0
	global_load_lds_dwordx4 v166, s[90:91]
	s_addc_u32 s53, s91, 0
	s_mov_b32 m0, s47
	s_nop 0
	global_load_lds_dwordx4 v166, s[52:53]
	s_add_u32 s52, s90, 0x4000
	s_addc_u32 s53, s91, 0
	s_mov_b32 m0, s58
	s_nop 0
	global_load_lds_dwordx4 v166, s[52:53]
	s_add_u32 s52, s90, 0x6000
	s_addc_u32 s53, s91, 0
	s_mov_b32 m0, s59
	s_nop 0
	global_load_lds_dwordx4 v166, s[52:53]
	s_add_u32 s52, s48, 0x2000
	s_mov_b32 m0, s57
	s_nop 0
	global_load_lds_dwordx4 v166, s[48:49]
	s_addc_u32 s53, s49, 0
	s_mov_b32 m0, s60
	s_nop 0
	global_load_lds_dwordx4 v166, s[52:53]
	s_waitcnt vmcnt(8)
	s_waitcnt lgkmcnt(0)
	s_barrier
	s_setprio 1
	s_waitcnt lgkmcnt(7)
	s_waitcnt lgkmcnt(0)
	v_mfma_f32_16x16x32_bf16 v[48:51], v[128:131], v[176:179], v[48:51]
	v_mfma_f32_16x16x32_bf16 v[48:51], v[132:135], v[180:183], v[48:51]
	v_mfma_f32_16x16x32_bf16 v[32:35], v[128:131], v[184:187], v[32:35]
	v_mfma_f32_16x16x32_bf16 v[32:35], v[132:135], v[188:191], v[32:35]
	v_mfma_f32_16x16x32_bf16 v[16:19], v[128:131], v[192:195], v[16:19]
	v_mfma_f32_16x16x32_bf16 v[16:19], v[132:135], v[196:199], v[16:19]
	v_mfma_f32_16x16x32_bf16 v[0:3], v[128:131], v[200:203], v[0:3]
	v_mfma_f32_16x16x32_bf16 v[0:3], v[132:135], v[204:207], v[0:3]
	v_mfma_f32_16x16x32_bf16 v[8:11], v[136:139], v[200:203], v[8:11]
	v_mfma_f32_16x16x32_bf16 v[8:11], v[140:143], v[204:207], v[8:11]
	v_mfma_f32_16x16x32_bf16 v[24:27], v[136:139], v[192:195], v[24:27]
	v_mfma_f32_16x16x32_bf16 v[24:27], v[140:143], v[196:199], v[24:27]
	v_mfma_f32_16x16x32_bf16 v[40:43], v[136:139], v[184:187], v[40:43]
	v_mfma_f32_16x16x32_bf16 v[40:43], v[140:143], v[188:191], v[40:43]
	v_mfma_f32_16x16x32_bf16 v[56:59], v[136:139], v[176:179], v[56:59]
	v_mfma_f32_16x16x32_bf16 v[56:59], v[140:143], v[180:183], v[56:59]
	s_setprio 0
	s_setprio 1
	s_waitcnt lgkmcnt(0)
	v_mfma_f32_16x16x32_bf16 v[52:55], v[152:155], v[176:179], v[52:55]
	v_mfma_f32_16x16x32_bf16 v[52:55], v[156:159], v[180:183], v[52:55]
	v_mfma_f32_16x16x32_bf16 v[36:39], v[152:155], v[184:187], v[36:39]
	v_mfma_f32_16x16x32_bf16 v[36:39], v[156:159], v[188:191], v[36:39]
	v_mfma_f32_16x16x32_bf16 v[20:23], v[152:155], v[192:195], v[20:23]
	v_mfma_f32_16x16x32_bf16 v[20:23], v[156:159], v[196:199], v[20:23]
	v_mfma_f32_16x16x32_bf16 v[4:7], v[152:155], v[200:203], v[4:7]
	v_mfma_f32_16x16x32_bf16 v[4:7], v[156:159], v[204:207], v[4:7]
	v_mfma_f32_16x16x32_bf16 v[12:15], v[160:163], v[200:203], v[12:15]
	v_mfma_f32_16x16x32_bf16 v[12:15], v[172:175], v[204:207], v[12:15]
	v_mfma_f32_16x16x32_bf16 v[28:31], v[160:163], v[192:195], v[28:31]
	v_mfma_f32_16x16x32_bf16 v[28:31], v[172:175], v[196:199], v[28:31]
	v_mfma_f32_16x16x32_bf16 v[44:47], v[160:163], v[184:187], v[44:47]
	v_mfma_f32_16x16x32_bf16 v[44:47], v[172:175], v[188:191], v[44:47]
	v_mfma_f32_16x16x32_bf16 v[64:67], v[160:163], v[176:179], v[64:67]
	v_mfma_f32_16x16x32_bf16 v[64:67], v[172:175], v[180:183], v[64:67]
	s_setprio 0
	s_barrier
	ds_read_b128 v[128:131], v148
	ds_read_b128 v[132:135], v148 offset:1024
	ds_read_b128 v[136:139], v148 offset:2048
	ds_read_b128 v[140:143], v148 offset:3072
	ds_read_b128 v[152:155], v150
	ds_read_b128 v[156:159], v150 offset:1024
	ds_read_b128 v[160:163], v150 offset:2048
	ds_read_b128 v[172:175], v150 offset:3072
	ds_read_b128 v[176:179], v170 offset:32768
	ds_read_b128 v[180:183], v170 offset:33792
	ds_read_b128 v[184:187], v170 offset:34816
	ds_read_b128 v[188:191], v170 offset:35840
	ds_read_b128 v[192:195], v170 offset:36864
	ds_read_b128 v[196:199], v170 offset:37888
	ds_read_b128 v[200:203], v170 offset:38912
	ds_read_b128 v[204:207], v170 offset:39936
	s_add_u32 s52, s48, 0x4000
	s_addc_u32 s53, s49, 0
	s_mov_b32 m0, s61
	s_nop 0
	global_load_lds_dwordx4 v166, s[52:53]
	s_add_u32 s52, s48, 0x6000
	s_addc_u32 s53, s49, 0
	s_mov_b32 m0, s62
	s_nop 0
	global_load_lds_dwordx4 v166, s[52:53]
	s_waitcnt vmcnt(8)
	s_waitcnt lgkmcnt(0)
	s_barrier
	s_setprio 1
	s_waitcnt lgkmcnt(7)
	s_waitcnt lgkmcnt(0)
	v_mfma_f32_16x16x32_bf16 v[112:115], v[128:131], v[176:179], v[112:115]
	v_mfma_f32_16x16x32_bf16 v[112:115], v[132:135], v[180:183], v[112:115]
	v_mfma_f32_16x16x32_bf16 v[96:99], v[128:131], v[184:187], v[96:99]
	v_mfma_f32_16x16x32_bf16 v[96:99], v[132:135], v[188:191], v[96:99]
	v_mfma_f32_16x16x32_bf16 v[80:83], v[128:131], v[192:195], v[80:83]
	v_mfma_f32_16x16x32_bf16 v[80:83], v[132:135], v[196:199], v[80:83]
	v_mfma_f32_16x16x32_bf16 v[60:63], v[128:131], v[200:203], v[60:63]
	v_mfma_f32_16x16x32_bf16 v[60:63], v[132:135], v[204:207], v[60:63]
	v_mfma_f32_16x16x32_bf16 v[72:75], v[136:139], v[200:203], v[72:75]
	v_mfma_f32_16x16x32_bf16 v[72:75], v[140:143], v[204:207], v[72:75]
	v_mfma_f32_16x16x32_bf16 v[88:91], v[136:139], v[192:195], v[88:91]
	v_mfma_f32_16x16x32_bf16 v[88:91], v[140:143], v[196:199], v[88:91]
	v_mfma_f32_16x16x32_bf16 v[104:107], v[136:139], v[184:187], v[104:107]
	v_mfma_f32_16x16x32_bf16 v[104:107], v[140:143], v[188:191], v[104:107]
	v_mfma_f32_16x16x32_bf16 v[120:123], v[136:139], v[176:179], v[120:123]
	v_mfma_f32_16x16x32_bf16 v[120:123], v[140:143], v[180:183], v[120:123]
	s_setprio 0
	s_setprio 1
	s_waitcnt lgkmcnt(0)
	v_mfma_f32_16x16x32_bf16 v[116:119], v[152:155], v[176:179], v[116:119]
	v_mfma_f32_16x16x32_bf16 v[116:119], v[156:159], v[180:183], v[116:119]
	v_mfma_f32_16x16x32_bf16 v[100:103], v[152:155], v[184:187], v[100:103]
	v_mfma_f32_16x16x32_bf16 v[100:103], v[156:159], v[188:191], v[100:103]
	v_mfma_f32_16x16x32_bf16 v[84:87], v[152:155], v[192:195], v[84:87]
	v_mfma_f32_16x16x32_bf16 v[84:87], v[156:159], v[196:199], v[84:87]
	v_mfma_f32_16x16x32_bf16 v[68:71], v[152:155], v[200:203], v[68:71]
	v_mfma_f32_16x16x32_bf16 v[68:71], v[156:159], v[204:207], v[68:71]
	v_mfma_f32_16x16x32_bf16 v[76:79], v[160:163], v[200:203], v[76:79]
	v_mfma_f32_16x16x32_bf16 v[76:79], v[172:175], v[204:207], v[76:79]
	v_mfma_f32_16x16x32_bf16 v[92:95], v[160:163], v[192:195], v[92:95]
	v_mfma_f32_16x16x32_bf16 v[92:95], v[172:175], v[196:199], v[92:95]
	v_mfma_f32_16x16x32_bf16 v[108:111], v[160:163], v[184:187], v[108:111]
	v_mfma_f32_16x16x32_bf16 v[108:111], v[172:175], v[188:191], v[108:111]
	v_mfma_f32_16x16x32_bf16 v[124:127], v[160:163], v[176:179], v[124:127]
	v_mfma_f32_16x16x32_bf16 v[124:127], v[172:175], v[180:183], v[124:127]
	s_setprio 0
	s_barrier
	s_add_u32 s52, s90, 0xa000
	ds_read_b128 v[176:179], v170 offset:49152
	ds_read_b128 v[180:183], v170 offset:50176
	ds_read_b128 v[184:187], v170 offset:51200
	ds_read_b128 v[188:191], v170 offset:52224
	ds_read_b128 v[192:195], v170 offset:53248
	ds_read_b128 v[196:199], v170 offset:54272
	ds_read_b128 v[200:203], v170 offset:55296
	ds_read_b128 v[204:207], v170 offset:56320
	s_mov_b32 m0, s66
	s_nop 0
	global_load_lds_dwordx4 v166, s[92:93]
	s_addc_u32 s53, s91, 0
	s_mov_b32 m0, s67
	s_nop 0
	global_load_lds_dwordx4 v166, s[52:53]
	s_add_u32 s52, s90, 0xc000
	s_addc_u32 s53, s91, 0
	s_mov_b32 m0, s70
	s_nop 0
	global_load_lds_dwordx4 v166, s[52:53]
	s_add_u32 s52, s90, 0xe000
	s_addc_u32 s53, s91, 0
	s_mov_b32 m0, s71
	s_nop 0
	global_load_lds_dwordx4 v166, s[52:53]
	s_add_u32 s48, s48, 0xa000
	s_mov_b32 m0, s68
	s_nop 0
	global_load_lds_dwordx4 v166, s[80:81]
	s_addc_u32 s49, s49, 0
	s_mov_b32 m0, s69
	s_nop 0
	global_load_lds_dwordx4 v166, s[48:49]
	s_waitcnt vmcnt(8)
	s_waitcnt lgkmcnt(0)
	s_barrier
	s_setprio 1
	s_waitcnt lgkmcnt(7)
	s_waitcnt lgkmcnt(0)
	v_mfma_f32_16x16x32_bf16 v[48:51], v[128:131], v[176:179], v[48:51]
	v_mfma_f32_16x16x32_bf16 v[48:51], v[132:135], v[180:183], v[48:51]
	v_mfma_f32_16x16x32_bf16 v[32:35], v[128:131], v[184:187], v[32:35]
	v_mfma_f32_16x16x32_bf16 v[32:35], v[132:135], v[188:191], v[32:35]
	v_mfma_f32_16x16x32_bf16 v[16:19], v[128:131], v[192:195], v[16:19]
	v_mfma_f32_16x16x32_bf16 v[16:19], v[132:135], v[196:199], v[16:19]
	v_mfma_f32_16x16x32_bf16 v[0:3], v[128:131], v[200:203], v[0:3]
	v_mfma_f32_16x16x32_bf16 v[0:3], v[132:135], v[204:207], v[0:3]
	v_mfma_f32_16x16x32_bf16 v[8:11], v[136:139], v[200:203], v[8:11]
	v_mfma_f32_16x16x32_bf16 v[8:11], v[140:143], v[204:207], v[8:11]
	v_mfma_f32_16x16x32_bf16 v[24:27], v[136:139], v[192:195], v[24:27]
	v_mfma_f32_16x16x32_bf16 v[24:27], v[140:143], v[196:199], v[24:27]
	v_mfma_f32_16x16x32_bf16 v[40:43], v[136:139], v[184:187], v[40:43]
	v_mfma_f32_16x16x32_bf16 v[40:43], v[140:143], v[188:191], v[40:43]
	v_mfma_f32_16x16x32_bf16 v[56:59], v[136:139], v[176:179], v[56:59]
	v_mfma_f32_16x16x32_bf16 v[56:59], v[140:143], v[180:183], v[56:59]
	s_setprio 0
	s_setprio 1
	s_waitcnt lgkmcnt(0)
	v_mfma_f32_16x16x32_bf16 v[52:55], v[152:155], v[176:179], v[52:55]
	v_mfma_f32_16x16x32_bf16 v[52:55], v[156:159], v[180:183], v[52:55]
	v_mfma_f32_16x16x32_bf16 v[36:39], v[152:155], v[184:187], v[36:39]
	v_mfma_f32_16x16x32_bf16 v[36:39], v[156:159], v[188:191], v[36:39]
	v_mfma_f32_16x16x32_bf16 v[20:23], v[152:155], v[192:195], v[20:23]
	v_mfma_f32_16x16x32_bf16 v[20:23], v[156:159], v[196:199], v[20:23]
	v_mfma_f32_16x16x32_bf16 v[4:7], v[152:155], v[200:203], v[4:7]
	v_mfma_f32_16x16x32_bf16 v[4:7], v[156:159], v[204:207], v[4:7]
	v_mfma_f32_16x16x32_bf16 v[12:15], v[160:163], v[200:203], v[12:15]
	v_mfma_f32_16x16x32_bf16 v[12:15], v[172:175], v[204:207], v[12:15]
	v_mfma_f32_16x16x32_bf16 v[28:31], v[160:163], v[192:195], v[28:31]
	v_mfma_f32_16x16x32_bf16 v[28:31], v[172:175], v[196:199], v[28:31]
	v_mfma_f32_16x16x32_bf16 v[44:47], v[160:163], v[184:187], v[44:47]
	v_mfma_f32_16x16x32_bf16 v[44:47], v[172:175], v[188:191], v[44:47]
	v_mfma_f32_16x16x32_bf16 v[64:67], v[160:163], v[176:179], v[64:67]
	v_mfma_f32_16x16x32_bf16 v[64:67], v[172:175], v[180:183], v[64:67]
	s_setprio 0
	s_barrier
	s_add_i32 s88, s88, 2
	s_add_u32 s54, s54, 0x10000
	s_addc_u32 s55, s55, 0
	s_cmp_gt_u32 s88, 61
	s_mov_b64 s[52:53], s[2:3]
	s_cbranch_scc0 .LBB0_170
	s_and_b64 vcc, exec, s[12:13]
	s_cbranch_vccz .LBB0_173
	s_barrier

.LBB0_326:
	ds_read_b128 v[60:63], v212
	ds_read_b128 v[68:71], v212 offset:1024
	ds_read_b128 v[88:91], v212 offset:2048
	ds_read_b128 v[92:95], v212 offset:3072
	ds_read_b128 v[112:115], v213
	ds_read_b128 v[116:119], v213 offset:1024
	ds_read_b128 v[138:141], v213 offset:2048
	ds_read_b128 v[152:155], v213 offset:3072
	s_cmpk_eq_i32 s80, 0xa8
	s_cselect_b32 s2, s4, s76
	s_cselect_b32 s3, s5, s77
	s_cselect_b32 s42, s38, s78
	s_cselect_b32 s43, s39, s79
	s_add_u32 s40, s2, 0x8000
	s_addc_u32 s41, s3, 0
	ds_read_b128 v[164:167], v214
	ds_read_b128 v[168:171], v214 offset:1024
	ds_read_b128 v[172:175], v214 offset:2048
	ds_read_b128 v[176:179], v214 offset:3072
	ds_read_b128 v[180:183], v214 offset:4096
	ds_read_b128 v[184:187], v214 offset:5120
	ds_read_b128 v[188:191], v214 offset:6144
	ds_read_b128 v[192:195], v214 offset:7168
	s_add_u32 s44, s76, 0xffffc000
	s_addc_u32 s45, s77, -1
	s_mov_b32 m0, s65
	s_nop 0
	global_load_lds_dwordx4 v210, s[44:45]
	s_add_u32 s44, s76, 0xffffe000
	s_addc_u32 s45, s77, -1
	s_mov_b32 m0, s68
	s_nop 0
	global_load_lds_dwordx4 v210, s[44:45]
	s_waitcnt vmcnt(8)
	s_waitcnt lgkmcnt(0)
	s_add_u32 s44, s42, 0x8000
	s_addc_u32 s45, s43, 0
	s_barrier
	s_setprio 1
	s_waitcnt lgkmcnt(7)
	s_waitcnt lgkmcnt(0)
	v_mfma_f32_16x16x32_bf16 v[160:163], v[60:63], v[164:167], v[160:163]
	v_mfma_f32_16x16x32_bf16 v[160:163], v[68:71], v[168:171], v[160:163]
	v_mfma_f32_16x16x32_bf16 v[132:135], v[60:63], v[172:175], v[132:135]
	v_mfma_f32_16x16x32_bf16 v[132:135], v[68:71], v[176:179], v[132:135]
	v_mfma_f32_16x16x32_bf16 v[108:111], v[60:63], v[180:183], v[108:111]
	v_mfma_f32_16x16x32_bf16 v[108:111], v[68:71], v[184:187], v[108:111]
	v_mfma_f32_16x16x32_bf16 v[84:87], v[60:63], v[188:191], v[84:87]
	v_mfma_f32_16x16x32_bf16 v[84:87], v[68:71], v[192:195], v[84:87]
	v_mfma_f32_16x16x32_bf16 v[80:83], v[88:91], v[188:191], v[80:83]
	v_mfma_f32_16x16x32_bf16 v[80:83], v[92:95], v[192:195], v[80:83]
	v_mfma_f32_16x16x32_bf16 v[104:107], v[88:91], v[180:183], v[104:107]
	v_mfma_f32_16x16x32_bf16 v[104:107], v[92:95], v[184:187], v[104:107]
	v_mfma_f32_16x16x32_bf16 v[128:131], v[88:91], v[172:175], v[128:131]
	v_mfma_f32_16x16x32_bf16 v[128:131], v[92:95], v[176:179], v[128:131]
	v_mfma_f32_16x16x32_bf16 v[156:159], v[88:91], v[164:167], v[156:159]
	v_mfma_f32_16x16x32_bf16 v[156:159], v[92:95], v[168:171], v[156:159]
	s_setprio 0
	s_setprio 1
	v_mfma_f32_16x16x32_bf16 v[148:151], v[112:115], v[164:167], v[148:151]
	v_mfma_f32_16x16x32_bf16 v[142:145], v[138:141], v[164:167], v[144:147]
	v_mfma_f32_16x16x32_bf16 v[124:127], v[112:115], v[172:175], v[124:127]
	v_mfma_f32_16x16x32_bf16 v[120:123], v[138:141], v[172:175], v[120:123]
	v_mfma_f32_16x16x32_bf16 v[100:103], v[112:115], v[180:183], v[100:103]
	v_mfma_f32_16x16x32_bf16 v[96:99], v[138:141], v[180:183], v[96:99]
	v_mfma_f32_16x16x32_bf16 v[76:79], v[112:115], v[188:191], v[76:79]
	v_mfma_f32_16x16x32_bf16 v[72:75], v[138:141], v[188:191], v[72:75]
	v_mfma_f32_16x16x32_bf16 v[148:151], v[116:119], v[168:171], v[148:151]
	v_mfma_f32_16x16x32_bf16 v[142:145], v[152:155], v[168:171], v[142:145]
	v_mfma_f32_16x16x32_bf16 v[124:127], v[116:119], v[176:179], v[124:127]
	v_mfma_f32_16x16x32_bf16 v[120:123], v[152:155], v[176:179], v[120:123]
	v_mfma_f32_16x16x32_bf16 v[100:103], v[116:119], v[184:187], v[100:103]
	v_mfma_f32_16x16x32_bf16 v[96:99], v[152:155], v[184:187], v[96:99]
	v_mfma_f32_16x16x32_bf16 v[76:79], v[116:119], v[192:195], v[76:79]
	v_mfma_f32_16x16x32_bf16 v[72:75], v[152:155], v[192:195], v[72:75]
	s_setprio 0
	s_barrier
	s_add_u32 s82, s42, 0x2000
	ds_read_b128 v[164:167], v214 offset:16384
	ds_read_b128 v[168:171], v214 offset:17408
	ds_read_b128 v[172:175], v214 offset:18432
	ds_read_b128 v[176:179], v214 offset:19456
	ds_read_b128 v[180:183], v214 offset:20480
	ds_read_b128 v[184:187], v214 offset:21504
	ds_read_b128 v[188:191], v214 offset:22528
	ds_read_b128 v[192:195], v214 offset:23552
	s_mov_b32 m0, s47
	s_nop 0
	global_load_lds_dwordx4 v210, s[42:43]
	s_addc_u32 s83, s43, 0
	s_mov_b32 m0, s48
	s_nop 0
	global_load_lds_dwordx4 v210, s[82:83]
	s_add_u32 s82, s42, 0x4000
	s_addc_u32 s83, s43, 0
	s_mov_b32 m0, s49
	s_nop 0
	global_load_lds_dwordx4 v210, s[82:83]
	s_add_u32 s82, s42, 0x6000
	s_addc_u32 s83, s43, 0
	s_mov_b32 m0, s52
	s_nop 0
	global_load_lds_dwordx4 v210, s[82:83]
	s_add_u32 s82, s2, 0x2000
	s_mov_b32 m0, s46
	s_nop 0
	global_load_lds_dwordx4 v210, s[2:3]
	s_addc_u32 s83, s3, 0
	s_mov_b32 m0, s53
	s_nop 0
	global_load_lds_dwordx4 v210, s[82:83]
	s_waitcnt vmcnt(8)
	s_waitcnt lgkmcnt(0)
	s_barrier
	s_setprio 1
	s_waitcnt lgkmcnt(7)
	s_waitcnt lgkmcnt(0)
	v_mfma_f32_16x16x32_bf16 v[64:67], v[60:63], v[164:167], v[64:67]
	v_mfma_f32_16x16x32_bf16 v[64:67], v[68:71], v[168:171], v[64:67]
	v_mfma_f32_16x16x32_bf16 v[44:47], v[60:63], v[172:175], v[44:47]
	v_mfma_f32_16x16x32_bf16 v[44:47], v[68:71], v[176:179], v[44:47]
	v_mfma_f32_16x16x32_bf16 v[28:31], v[60:63], v[180:183], v[28:31]
	v_mfma_f32_16x16x32_bf16 v[28:31], v[68:71], v[184:187], v[28:31]
	v_mfma_f32_16x16x32_bf16 v[12:15], v[60:63], v[188:191], v[12:15]
	v_mfma_f32_16x16x32_bf16 v[12:15], v[68:71], v[192:195], v[12:15]
	v_mfma_f32_16x16x32_bf16 v[8:11], v[88:91], v[188:191], v[8:11]
	v_mfma_f32_16x16x32_bf16 v[8:11], v[92:95], v[192:195], v[8:11]
	v_mfma_f32_16x16x32_bf16 v[24:27], v[88:91], v[180:183], v[24:27]
	v_mfma_f32_16x16x32_bf16 v[24:27], v[92:95], v[184:187], v[24:27]
	v_mfma_f32_16x16x32_bf16 v[40:43], v[88:91], v[172:175], v[40:43]
	v_mfma_f32_16x16x32_bf16 v[40:43], v[92:95], v[176:179], v[40:43]
	v_mfma_f32_16x16x32_bf16 v[56:59], v[88:91], v[164:167], v[56:59]
	v_mfma_f32_16x16x32_bf16 v[56:59], v[92:95], v[168:171], v[56:59]
	s_setprio 0
	s_setprio 1
	s_waitcnt lgkmcnt(0)
	v_mfma_f32_16x16x32_bf16 v[52:55], v[112:115], v[164:167], v[52:55]
	v_mfma_f32_16x16x32_bf16 v[52:55], v[116:119], v[168:171], v[52:55]
	v_mfma_f32_16x16x32_bf16 v[36:39], v[112:115], v[172:175], v[36:39]
	v_mfma_f32_16x16x32_bf16 v[36:39], v[116:119], v[176:179], v[36:39]
	v_mfma_f32_16x16x32_bf16 v[20:23], v[112:115], v[180:183], v[20:23]
	v_mfma_f32_16x16x32_bf16 v[20:23], v[116:119], v[184:187], v[20:23]
	v_mfma_f32_16x16x32_bf16 v[4:7], v[112:115], v[188:191], v[4:7]
	v_mfma_f32_16x16x32_bf16 v[4:7], v[116:119], v[192:195], v[4:7]
	v_mfma_f32_16x16x32_bf16 v[0:3], v[138:141], v[188:191], v[0:3]
	v_mfma_f32_16x16x32_bf16 v[0:3], v[152:155], v[192:195], v[0:3]
	v_mfma_f32_16x16x32_bf16 v[16:19], v[138:141], v[180:183], v[16:19]
	v_mfma_f32_16x16x32_bf16 v[16:19], v[152:155], v[184:187], v[16:19]
	v_mfma_f32_16x16x32_bf16 v[32:35], v[138:141], v[172:175], v[32:35]
	v_mfma_f32_16x16x32_bf16 v[32:35], v[152:155], v[176:179], v[32:35]
	v_mfma_f32_16x16x32_bf16 v[48:51], v[138:141], v[164:167], v[48:51]
	v_mfma_f32_16x16x32_bf16 v[48:51], v[152:155], v[168:171], v[48:51]
	s_setprio 0
	s_barrier
	ds_read_b128 v[60:63], v136
	ds_read_b128 v[68:71], v136 offset:1024
	ds_read_b128 v[88:91], v136 offset:2048
	ds_read_b128 v[92:95], v136 offset:3072
	ds_read_b128 v[112:115], v137
	ds_read_b128 v[116:119], v137 offset:1024
	ds_read_b128 v[138:141], v137 offset:2048
	ds_read_b128 v[152:155], v137 offset:3072
	ds_read_b128 v[164:167], v214 offset:32768
	ds_read_b128 v[168:171], v214 offset:33792
	ds_read_b128 v[172:175], v214 offset:34816
	ds_read_b128 v[176:179], v214 offset:35840
	ds_read_b128 v[180:183], v214 offset:36864
	ds_read_b128 v[184:187], v214 offset:37888
	ds_read_b128 v[188:191], v214 offset:38912
	ds_read_b128 v[192:195], v214 offset:39936
	s_add_u32 s82, s2, 0x4000
	s_addc_u32 s83, s3, 0
	s_mov_b32 m0, s54
	s_nop 0
	global_load_lds_dwordx4 v210, s[82:83]
	s_add_u32 s82, s2, 0x6000
	s_addc_u32 s83, s3, 0
	s_mov_b32 m0, s55
	s_nop 0
	global_load_lds_dwordx4 v210, s[82:83]
	s_waitcnt vmcnt(8)
	s_waitcnt lgkmcnt(0)
	s_barrier
	s_setprio 1
	s_waitcnt lgkmcnt(7)
	s_waitcnt lgkmcnt(0)
	v_mfma_f32_16x16x32_bf16 v[160:163], v[60:63], v[164:167], v[160:163]
	v_mfma_f32_16x16x32_bf16 v[160:163], v[68:71], v[168:171], v[160:163]
	v_mfma_f32_16x16x32_bf16 v[132:135], v[60:63], v[172:175], v[132:135]
	v_mfma_f32_16x16x32_bf16 v[132:135], v[68:71], v[176:179], v[132:135]
	v_mfma_f32_16x16x32_bf16 v[108:111], v[60:63], v[180:183], v[108:111]
	v_mfma_f32_16x16x32_bf16 v[108:111], v[68:71], v[184:187], v[108:111]
	v_mfma_f32_16x16x32_bf16 v[84:87], v[60:63], v[188:191], v[84:87]
	v_mfma_f32_16x16x32_bf16 v[84:87], v[68:71], v[192:195], v[84:87]
	v_mfma_f32_16x16x32_bf16 v[80:83], v[88:91], v[188:191], v[80:83]
	v_mfma_f32_16x16x32_bf16 v[80:83], v[92:95], v[192:195], v[80:83]
	v_mfma_f32_16x16x32_bf16 v[104:107], v[88:91], v[180:183], v[104:107]
	v_mfma_f32_16x16x32_bf16 v[104:107], v[92:95], v[184:187], v[104:107]
	v_mfma_f32_16x16x32_bf16 v[128:131], v[88:91], v[172:175], v[128:131]
	v_mfma_f32_16x16x32_bf16 v[128:131], v[92:95], v[176:179], v[128:131]
	v_mfma_f32_16x16x32_bf16 v[156:159], v[88:91], v[164:167], v[156:159]
	v_mfma_f32_16x16x32_bf16 v[156:159], v[92:95], v[168:171], v[156:159]
	s_setprio 0
	s_setprio 1
	v_mfma_f32_16x16x32_bf16 v[146:149], v[112:115], v[164:167], v[148:151]
	v_mfma_f32_16x16x32_bf16 v[142:145], v[138:141], v[164:167], v[142:145]
	v_mfma_f32_16x16x32_bf16 v[124:127], v[112:115], v[172:175], v[124:127]
	v_mfma_f32_16x16x32_bf16 v[120:123], v[138:141], v[172:175], v[120:123]
	v_mfma_f32_16x16x32_bf16 v[100:103], v[112:115], v[180:183], v[100:103]
	v_mfma_f32_16x16x32_bf16 v[96:99], v[138:141], v[180:183], v[96:99]
	v_mfma_f32_16x16x32_bf16 v[76:79], v[112:115], v[188:191], v[76:79]
	v_mfma_f32_16x16x32_bf16 v[72:75], v[138:141], v[188:191], v[72:75]
	v_mfma_f32_16x16x32_bf16 v[148:151], v[116:119], v[168:171], v[146:149]
	v_mfma_f32_16x16x32_bf16 v[144:147], v[152:155], v[168:171], v[142:145]
	v_mfma_f32_16x16x32_bf16 v[124:127], v[116:119], v[176:179], v[124:127]
	v_mfma_f32_16x16x32_bf16 v[120:123], v[152:155], v[176:179], v[120:123]
	v_mfma_f32_16x16x32_bf16 v[100:103], v[116:119], v[184:187], v[100:103]
	v_mfma_f32_16x16x32_bf16 v[96:99], v[152:155], v[184:187], v[96:99]
	v_mfma_f32_16x16x32_bf16 v[76:79], v[116:119], v[192:195], v[76:79]
	v_mfma_f32_16x16x32_bf16 v[72:75], v[152:155], v[192:195], v[72:75]
	s_setprio 0
	s_barrier
	ds_read_b128 v[164:167], v214 offset:49152
	ds_read_b128 v[168:171], v214 offset:50176
	ds_read_b128 v[172:175], v214 offset:51200
	ds_read_b128 v[176:179], v214 offset:52224
	ds_read_b128 v[180:183], v214 offset:53248
	ds_read_b128 v[184:187], v214 offset:54272
	ds_read_b128 v[188:191], v214 offset:55296
	ds_read_b128 v[192:195], v214 offset:56320
	s_mov_b32 m0, s59
	s_nop 0
	global_load_lds_dwordx4 v210, s[44:45]
	s_add_u32 s44, s42, 0xa000
	s_addc_u32 s45, s43, 0
	s_mov_b32 m0, s60
	s_nop 0
	global_load_lds_dwordx4 v210, s[44:45]
	s_add_u32 s44, s42, 0xc000
	s_addc_u32 s45, s43, 0
	s_mov_b32 m0, s63
	s_nop 0
	global_load_lds_dwordx4 v210, s[44:45]
	s_add_u32 s42, s42, 0xe000
	s_addc_u32 s43, s43, 0
	s_mov_b32 m0, s64
	s_nop 0
	global_load_lds_dwordx4 v210, s[42:43]
	s_add_u32 s2, s2, 0xa000
	s_mov_b32 m0, s61
	s_nop 0
	global_load_lds_dwordx4 v210, s[40:41]
	s_addc_u32 s3, s3, 0
	s_mov_b32 m0, s62
	s_nop 0
	global_load_lds_dwordx4 v210, s[2:3]
	s_waitcnt vmcnt(8)
	s_waitcnt lgkmcnt(0)
	s_barrier
	s_setprio 1
	s_waitcnt lgkmcnt(7)
	s_waitcnt lgkmcnt(0)
	v_mfma_f32_16x16x32_bf16 v[64:67], v[60:63], v[164:167], v[64:67]
	v_mfma_f32_16x16x32_bf16 v[64:67], v[68:71], v[168:171], v[64:67]
	v_mfma_f32_16x16x32_bf16 v[44:47], v[60:63], v[172:175], v[44:47]
	v_mfma_f32_16x16x32_bf16 v[44:47], v[68:71], v[176:179], v[44:47]
	v_mfma_f32_16x16x32_bf16 v[28:31], v[60:63], v[180:183], v[28:31]
	v_mfma_f32_16x16x32_bf16 v[28:31], v[68:71], v[184:187], v[28:31]
	v_mfma_f32_16x16x32_bf16 v[12:15], v[60:63], v[188:191], v[12:15]
	v_mfma_f32_16x16x32_bf16 v[12:15], v[68:71], v[192:195], v[12:15]
	v_mfma_f32_16x16x32_bf16 v[8:11], v[88:91], v[188:191], v[8:11]
	v_mfma_f32_16x16x32_bf16 v[8:11], v[92:95], v[192:195], v[8:11]
	v_mfma_f32_16x16x32_bf16 v[24:27], v[88:91], v[180:183], v[24:27]
	v_mfma_f32_16x16x32_bf16 v[24:27], v[92:95], v[184:187], v[24:27]
	v_mfma_f32_16x16x32_bf16 v[40:43], v[88:91], v[172:175], v[40:43]
	v_mfma_f32_16x16x32_bf16 v[40:43], v[92:95], v[176:179], v[40:43]
	v_mfma_f32_16x16x32_bf16 v[56:59], v[88:91], v[164:167], v[56:59]
	v_mfma_f32_16x16x32_bf16 v[56:59], v[92:95], v[168:171], v[56:59]
	s_setprio 0
	s_setprio 1
	s_waitcnt lgkmcnt(0)
	v_mfma_f32_16x16x32_bf16 v[52:55], v[112:115], v[164:167], v[52:55]
	v_mfma_f32_16x16x32_bf16 v[52:55], v[116:119], v[168:171], v[52:55]
	v_mfma_f32_16x16x32_bf16 v[36:39], v[112:115], v[172:175], v[36:39]
	v_mfma_f32_16x16x32_bf16 v[36:39], v[116:119], v[176:179], v[36:39]
	v_mfma_f32_16x16x32_bf16 v[20:23], v[112:115], v[180:183], v[20:23]
	v_mfma_f32_16x16x32_bf16 v[20:23], v[116:119], v[184:187], v[20:23]
	v_mfma_f32_16x16x32_bf16 v[4:7], v[112:115], v[188:191], v[4:7]
	v_mfma_f32_16x16x32_bf16 v[4:7], v[116:119], v[192:195], v[4:7]
	v_mfma_f32_16x16x32_bf16 v[0:3], v[138:141], v[188:191], v[0:3]
	v_mfma_f32_16x16x32_bf16 v[0:3], v[152:155], v[192:195], v[0:3]
	v_mfma_f32_16x16x32_bf16 v[16:19], v[138:141], v[180:183], v[16:19]
	v_mfma_f32_16x16x32_bf16 v[16:19], v[152:155], v[184:187], v[16:19]
	v_mfma_f32_16x16x32_bf16 v[32:35], v[138:141], v[172:175], v[32:35]
	v_mfma_f32_16x16x32_bf16 v[32:35], v[152:155], v[176:179], v[32:35]
	v_mfma_f32_16x16x32_bf16 v[48:51], v[138:141], v[164:167], v[48:51]
	v_mfma_f32_16x16x32_bf16 v[48:51], v[152:155], v[168:171], v[48:51]
	s_setprio 0
	s_barrier
	s_add_i32 s80, s80, 2
	s_add_u32 s76, s76, 0x10000
	s_addc_u32 s77, s77, 0
	s_add_u32 s78, s78, 0x10000
	s_addc_u32 s79, s79, 0
	s_cmpk_gt_u32 s80, 0xa9
	s_cbranch_scc0 .LBB0_326
	s_and_b64 vcc, exec, s[12:13]
	s_cbranch_vccz .LBB0_329
	s_barrier

.LBB0_421:
	s_add_u32 s8, s48, 0x10000
	s_waitcnt lgkmcnt(0)
	s_addc_u32 s9, s49, 0
	s_add_u32 s52, s80, 0x10000
	s_addc_u32 s53, s81, 0
	s_barrier
	s_setprio 1
	s_waitcnt lgkmcnt(7)
	s_waitcnt lgkmcnt(0)
	v_mfma_f32_16x16x32_bf16 v[32:35], v[16:19], v[68:71], 0
	v_mfma_f32_16x16x32_bf16 v[32:35], v[20:23], v[80:83], v[32:35]
	v_mfma_f32_16x16x32_bf16 v[40:43], v[16:19], v[84:87], 0
	v_mfma_f32_16x16x32_bf16 v[40:43], v[20:23], v[96:99], v[40:43]
	v_mfma_f32_16x16x32_bf16 v[48:51], v[16:19], v[88:91], 0
	v_mfma_f32_16x16x32_bf16 v[48:51], v[20:23], v[92:95], v[48:51]
	v_mfma_f32_16x16x32_bf16 v[56:59], v[16:19], v[72:75], 0
	v_mfma_f32_16x16x32_bf16 v[56:59], v[20:23], v[76:79], v[56:59]
	v_mfma_f32_16x16x32_bf16 v[60:63], v[24:27], v[72:75], 0
	v_mfma_f32_16x16x32_bf16 v[60:63], v[28:31], v[76:79], v[60:63]
	v_mfma_f32_16x16x32_bf16 v[52:55], v[24:27], v[88:91], 0
	v_mfma_f32_16x16x32_bf16 v[52:55], v[28:31], v[92:95], v[52:55]
	v_mfma_f32_16x16x32_bf16 v[44:47], v[24:27], v[84:87], 0
	v_mfma_f32_16x16x32_bf16 v[44:47], v[28:31], v[96:99], v[44:47]
	v_mfma_f32_16x16x32_bf16 v[36:39], v[24:27], v[68:71], 0
	v_mfma_f32_16x16x32_bf16 v[36:39], v[28:31], v[80:83], v[36:39]
	s_setprio 0
	s_setprio 1
	v_mfma_f32_16x16x32_bf16 v[64:67], v[0:3], v[68:71], 0
	v_mfma_f32_16x16x32_bf16 v[68:71], v[8:11], v[68:71], 0
	v_mfma_f32_16x16x32_bf16 v[64:67], v[4:7], v[80:83], v[64:67]
	v_mfma_f32_16x16x32_bf16 v[68:71], v[12:15], v[80:83], v[68:71]
	v_mfma_f32_16x16x32_bf16 v[80:83], v[0:3], v[84:87], 0
	v_mfma_f32_16x16x32_bf16 v[84:87], v[8:11], v[84:87], 0
	v_mfma_f32_16x16x32_bf16 v[80:83], v[4:7], v[96:99], v[80:83]
	v_mfma_f32_16x16x32_bf16 v[84:87], v[12:15], v[96:99], v[84:87]
	v_mfma_f32_16x16x32_bf16 v[96:99], v[0:3], v[88:91], 0
	v_mfma_f32_16x16x32_bf16 v[88:91], v[8:11], v[88:91], 0
	v_mfma_f32_16x16x32_bf16 v[132:135], v[12:15], v[92:95], v[88:91]
	v_mfma_f32_16x16x32_bf16 v[88:91], v[0:3], v[72:75], 0
	v_mfma_f32_16x16x32_bf16 v[72:75], v[8:11], v[72:75], 0
	v_mfma_f32_16x16x32_bf16 v[128:131], v[4:7], v[92:95], v[96:99]
	v_mfma_f32_16x16x32_bf16 v[136:139], v[4:7], v[76:79], v[88:91]
	v_mfma_f32_16x16x32_bf16 v[140:143], v[12:15], v[76:79], v[72:75]
	s_setprio 0
	s_barrier
	ds_read_b128 v[104:107], v164 offset:16384
	ds_read_b128 v[108:111], v164 offset:17408
	ds_read_b128 v[96:99], v164 offset:18432
	ds_read_b128 v[100:103], v164 offset:19456
	ds_read_b128 v[88:91], v164 offset:20480
	ds_read_b128 v[92:95], v164 offset:21504
	ds_read_b128 v[72:75], v164 offset:22528
	ds_read_b128 v[76:79], v164 offset:23552
	s_mov_b32 m0, s55
	s_nop 0
	global_load_lds_dwordx4 v160, s[52:53]
	s_add_u32 s52, s80, 0x12000
	s_addc_u32 s53, s81, 0
	s_mov_b32 m0, s56
	s_nop 0
	global_load_lds_dwordx4 v160, s[52:53]
	s_add_u32 s52, s80, 0x14000
	s_addc_u32 s53, s81, 0
	s_mov_b32 m0, s57
	s_nop 0
	global_load_lds_dwordx4 v160, s[52:53]
	s_add_u32 s52, s80, 0x16000
	s_addc_u32 s53, s81, 0
	s_mov_b32 m0, s58
	s_nop 0
	global_load_lds_dwordx4 v160, s[52:53]
	s_nop 0
	s_mov_b32 m0, s54
	s_nop 0
	global_load_lds_dwordx4 v160, s[8:9]
	s_add_u32 s8, s48, 0x12000
	s_addc_u32 s9, s49, 0
	s_mov_b32 m0, s59
	s_nop 0
	global_load_lds_dwordx4 v160, s[8:9]
	s_and_b64 vcc, exec, s[2:3]
	s_cbranch_vccz .LBB0_496
	s_waitcnt vmcnt(24)
	s_cbranch_execnz .LBB0_424

.LBB0_425:
	ds_read_b128 v[128:131], v162
	ds_read_b128 v[132:135], v162 offset:1024
	ds_read_b128 v[136:139], v162 offset:2048
	ds_read_b128 v[140:143], v162 offset:3072
	ds_read_b128 v[152:155], v163
	ds_read_b128 v[156:159], v163 offset:1024
	ds_read_b128 v[168:171], v163 offset:2048
	ds_read_b128 v[172:175], v163 offset:3072
	s_add_u32 s48, s52, 0x10000
	s_addc_u32 s49, s53, 0
	s_cmp_eq_u32 s79, 60
	s_cselect_b32 s80, s10, s48
	s_cselect_b32 s81, s5, s49
	s_cselect_b32 s96, s47, s77
	s_cselect_b32 s97, s45, s78
	s_add_u32 s2, s80, 0x8000
	s_addc_u32 s3, s81, 0
	ds_read_b128 v[176:179], v164
	ds_read_b128 v[180:183], v164 offset:1024
	ds_read_b128 v[184:187], v164 offset:2048
	ds_read_b128 v[188:191], v164 offset:3072
	ds_read_b128 v[192:195], v164 offset:4096
	ds_read_b128 v[196:199], v164 offset:5120
	ds_read_b128 v[200:203], v164 offset:6144
	ds_read_b128 v[204:207], v164 offset:7168
	s_add_u32 s82, s52, 0xc000
	s_addc_u32 s83, s53, 0
	s_mov_b32 m0, s70
	s_nop 0
	global_load_lds_dwordx4 v160, s[82:83]
	s_add_u32 s52, s52, 0xe000
	s_addc_u32 s53, s53, 0
	s_mov_b32 m0, s71
	s_nop 0
	global_load_lds_dwordx4 v160, s[52:53]
	s_waitcnt vmcnt(8)
	s_waitcnt lgkmcnt(0)
	s_add_u32 s52, s96, 0x8000
	s_addc_u32 s53, s97, 0
	s_barrier
	s_setprio 1
	s_waitcnt lgkmcnt(7)
	s_waitcnt lgkmcnt(0)
	v_mfma_f32_16x16x32_bf16 v[124:127], v[128:131], v[176:179], v[124:127]
	v_mfma_f32_16x16x32_bf16 v[124:127], v[132:135], v[180:183], v[124:127]
	v_mfma_f32_16x16x32_bf16 v[108:111], v[128:131], v[184:187], v[108:111]
	v_mfma_f32_16x16x32_bf16 v[108:111], v[132:135], v[188:191], v[108:111]
	v_mfma_f32_16x16x32_bf16 v[92:95], v[128:131], v[192:195], v[92:95]
	v_mfma_f32_16x16x32_bf16 v[92:95], v[132:135], v[196:199], v[92:95]
	v_mfma_f32_16x16x32_bf16 v[76:79], v[128:131], v[200:203], v[76:79]
	v_mfma_f32_16x16x32_bf16 v[76:79], v[132:135], v[204:207], v[76:79]
	v_mfma_f32_16x16x32_bf16 v[72:75], v[136:139], v[200:203], v[72:75]
	v_mfma_f32_16x16x32_bf16 v[72:75], v[140:143], v[204:207], v[72:75]
	v_mfma_f32_16x16x32_bf16 v[88:91], v[136:139], v[192:195], v[88:91]
	v_mfma_f32_16x16x32_bf16 v[88:91], v[140:143], v[196:199], v[88:91]
	v_mfma_f32_16x16x32_bf16 v[104:107], v[136:139], v[184:187], v[104:107]
	v_mfma_f32_16x16x32_bf16 v[104:107], v[140:143], v[188:191], v[104:107]
	v_mfma_f32_16x16x32_bf16 v[120:123], v[136:139], v[176:179], v[120:123]
	v_mfma_f32_16x16x32_bf16 v[120:123], v[140:143], v[180:183], v[120:123]
	s_setprio 0
	s_setprio 1
	s_waitcnt lgkmcnt(0)
	v_mfma_f32_16x16x32_bf16 v[116:119], v[152:155], v[176:179], v[116:119]
	v_mfma_f32_16x16x32_bf16 v[116:119], v[156:159], v[180:183], v[116:119]
	v_mfma_f32_16x16x32_bf16 v[100:103], v[152:155], v[184:187], v[100:103]
	v_mfma_f32_16x16x32_bf16 v[100:103], v[156:159], v[188:191], v[100:103]
	v_mfma_f32_16x16x32_bf16 v[84:87], v[152:155], v[192:195], v[84:87]
	v_mfma_f32_16x16x32_bf16 v[84:87], v[156:159], v[196:199], v[84:87]
	v_mfma_f32_16x16x32_bf16 v[68:71], v[152:155], v[200:203], v[68:71]
	v_mfma_f32_16x16x32_bf16 v[68:71], v[156:159], v[204:207], v[68:71]
	v_mfma_f32_16x16x32_bf16 v[64:67], v[168:171], v[200:203], v[64:67]
	v_mfma_f32_16x16x32_bf16 v[64:67], v[172:175], v[204:207], v[64:67]
	v_mfma_f32_16x16x32_bf16 v[80:83], v[168:171], v[192:195], v[80:83]
	v_mfma_f32_16x16x32_bf16 v[80:83], v[172:175], v[196:199], v[80:83]
	v_mfma_f32_16x16x32_bf16 v[96:99], v[168:171], v[184:187], v[96:99]
	v_mfma_f32_16x16x32_bf16 v[96:99], v[172:175], v[188:191], v[96:99]
	v_mfma_f32_16x16x32_bf16 v[112:115], v[168:171], v[176:179], v[112:115]
	v_mfma_f32_16x16x32_bf16 v[112:115], v[172:175], v[180:183], v[112:115]
	s_setprio 0
	s_barrier
	s_add_u32 s82, s96, 0x2000
	ds_read_b128 v[176:179], v164 offset:16384
	ds_read_b128 v[180:183], v164 offset:17408
	ds_read_b128 v[184:187], v164 offset:18432
	ds_read_b128 v[188:191], v164 offset:19456
	ds_read_b128 v[192:195], v164 offset:20480
	ds_read_b128 v[196:199], v164 offset:21504
	ds_read_b128 v[200:203], v164 offset:22528
	ds_read_b128 v[204:207], v164 offset:23552
	s_mov_b32 m0, s55
	s_nop 0
	global_load_lds_dwordx4 v160, s[96:97]
	s_addc_u32 s83, s97, 0
	s_mov_b32 m0, s56
	s_nop 0
	global_load_lds_dwordx4 v160, s[82:83]
	s_add_u32 s82, s96, 0x4000
	s_addc_u32 s83, s97, 0
	s_mov_b32 m0, s57
	s_nop 0
	global_load_lds_dwordx4 v160, s[82:83]
	s_add_u32 s82, s96, 0x6000
	s_addc_u32 s83, s97, 0
	s_mov_b32 m0, s58
	s_nop 0
	global_load_lds_dwordx4 v160, s[82:83]
	s_add_u32 s82, s80, 0x2000
	s_mov_b32 m0, s54
	s_nop 0
	global_load_lds_dwordx4 v160, s[80:81]
	s_addc_u32 s83, s81, 0
	s_mov_b32 m0, s59
	s_nop 0
	global_load_lds_dwordx4 v160, s[82:83]
	s_waitcnt vmcnt(8)
	s_waitcnt lgkmcnt(0)
	s_barrier
	s_setprio 1
	s_waitcnt lgkmcnt(7)
	s_waitcnt lgkmcnt(0)
	v_mfma_f32_16x16x32_bf16 v[60:63], v[128:131], v[176:179], v[60:63]
	v_mfma_f32_16x16x32_bf16 v[60:63], v[132:135], v[180:183], v[60:63]
	v_mfma_f32_16x16x32_bf16 v[44:47], v[128:131], v[184:187], v[44:47]
	v_mfma_f32_16x16x32_bf16 v[44:47], v[132:135], v[188:191], v[44:47]
	v_mfma_f32_16x16x32_bf16 v[28:31], v[128:131], v[192:195], v[28:31]
	v_mfma_f32_16x16x32_bf16 v[28:31], v[132:135], v[196:199], v[28:31]
	v_mfma_f32_16x16x32_bf16 v[12:15], v[128:131], v[200:203], v[12:15]
	v_mfma_f32_16x16x32_bf16 v[12:15], v[132:135], v[204:207], v[12:15]
	v_mfma_f32_16x16x32_bf16 v[8:11], v[136:139], v[200:203], v[8:11]
	v_mfma_f32_16x16x32_bf16 v[8:11], v[140:143], v[204:207], v[8:11]
	v_mfma_f32_16x16x32_bf16 v[24:27], v[136:139], v[192:195], v[24:27]
	v_mfma_f32_16x16x32_bf16 v[24:27], v[140:143], v[196:199], v[24:27]
	v_mfma_f32_16x16x32_bf16 v[40:43], v[136:139], v[184:187], v[40:43]
	v_mfma_f32_16x16x32_bf16 v[40:43], v[140:143], v[188:191], v[40:43]
	v_mfma_f32_16x16x32_bf16 v[56:59], v[136:139], v[176:179], v[56:59]
	v_mfma_f32_16x16x32_bf16 v[56:59], v[140:143], v[180:183], v[56:59]
	s_setprio 0
	s_setprio 1
	s_waitcnt lgkmcnt(0)
	v_mfma_f32_16x16x32_bf16 v[52:55], v[152:155], v[176:179], v[52:55]
	v_mfma_f32_16x16x32_bf16 v[52:55], v[156:159], v[180:183], v[52:55]
	v_mfma_f32_16x16x32_bf16 v[36:39], v[152:155], v[184:187], v[36:39]
	v_mfma_f32_16x16x32_bf16 v[36:39], v[156:159], v[188:191], v[36:39]
	v_mfma_f32_16x16x32_bf16 v[20:23], v[152:155], v[192:195], v[20:23]
	v_mfma_f32_16x16x32_bf16 v[20:23], v[156:159], v[196:199], v[20:23]
	v_mfma_f32_16x16x32_bf16 v[4:7], v[152:155], v[200:203], v[4:7]
	v_mfma_f32_16x16x32_bf16 v[4:7], v[156:159], v[204:207], v[4:7]
	v_mfma_f32_16x16x32_bf16 v[0:3], v[168:171], v[200:203], v[0:3]
	v_mfma_f32_16x16x32_bf16 v[0:3], v[172:175], v[204:207], v[0:3]
	v_mfma_f32_16x16x32_bf16 v[16:19], v[168:171], v[192:195], v[16:19]
	v_mfma_f32_16x16x32_bf16 v[16:19], v[172:175], v[196:199], v[16:19]
	v_mfma_f32_16x16x32_bf16 v[32:35], v[168:171], v[184:187], v[32:35]
	v_mfma_f32_16x16x32_bf16 v[32:35], v[172:175], v[188:191], v[32:35]
	v_mfma_f32_16x16x32_bf16 v[48:51], v[168:171], v[176:179], v[48:51]
	v_mfma_f32_16x16x32_bf16 v[48:51], v[172:175], v[180:183], v[48:51]
	s_setprio 0
	s_barrier
	ds_read_b128 v[128:131], v148
	ds_read_b128 v[132:135], v148 offset:1024
	ds_read_b128 v[136:139], v148 offset:2048
	ds_read_b128 v[140:143], v148 offset:3072
	ds_read_b128 v[152:155], v150
	ds_read_b128 v[156:159], v150 offset:1024
	ds_read_b128 v[168:171], v150 offset:2048
	ds_read_b128 v[172:175], v150 offset:3072
	ds_read_b128 v[176:179], v164 offset:32768
	ds_read_b128 v[180:183], v164 offset:33792
	ds_read_b128 v[184:187], v164 offset:34816
	ds_read_b128 v[188:191], v164 offset:35840
	ds_read_b128 v[192:195], v164 offset:36864
	ds_read_b128 v[196:199], v164 offset:37888
	ds_read_b128 v[200:203], v164 offset:38912
	ds_read_b128 v[204:207], v164 offset:39936
	s_add_u32 s82, s80, 0x4000
	s_addc_u32 s83, s81, 0
	s_mov_b32 m0, s60
	s_nop 0
	global_load_lds_dwordx4 v160, s[82:83]
	s_add_u32 s82, s80, 0x6000
	s_addc_u32 s83, s81, 0
	s_mov_b32 m0, s61
	s_nop 0
	global_load_lds_dwordx4 v160, s[82:83]
	s_waitcnt vmcnt(8)
	s_waitcnt lgkmcnt(0)
	s_barrier
	s_setprio 1
	s_waitcnt lgkmcnt(7)
	s_waitcnt lgkmcnt(0)
	v_mfma_f32_16x16x32_bf16 v[124:127], v[128:131], v[176:179], v[124:127]
	v_mfma_f32_16x16x32_bf16 v[124:127], v[132:135], v[180:183], v[124:127]
	v_mfma_f32_16x16x32_bf16 v[108:111], v[128:131], v[184:187], v[108:111]
	v_mfma_f32_16x16x32_bf16 v[108:111], v[132:135], v[188:191], v[108:111]
	v_mfma_f32_16x16x32_bf16 v[92:95], v[128:131], v[192:195], v[92:95]
	v_mfma_f32_16x16x32_bf16 v[92:95], v[132:135], v[196:199], v[92:95]
	v_mfma_f32_16x16x32_bf16 v[76:79], v[128:131], v[200:203], v[76:79]
	v_mfma_f32_16x16x32_bf16 v[76:79], v[132:135], v[204:207], v[76:79]
	v_mfma_f32_16x16x32_bf16 v[72:75], v[136:139], v[200:203], v[72:75]
	v_mfma_f32_16x16x32_bf16 v[72:75], v[140:143], v[204:207], v[72:75]
	v_mfma_f32_16x16x32_bf16 v[88:91], v[136:139], v[192:195], v[88:91]
	v_mfma_f32_16x16x32_bf16 v[88:91], v[140:143], v[196:199], v[88:91]
	v_mfma_f32_16x16x32_bf16 v[104:107], v[136:139], v[184:187], v[104:107]
	v_mfma_f32_16x16x32_bf16 v[104:107], v[140:143], v[188:191], v[104:107]
	v_mfma_f32_16x16x32_bf16 v[120:123], v[136:139], v[176:179], v[120:123]
	v_mfma_f32_16x16x32_bf16 v[120:123], v[140:143], v[180:183], v[120:123]
	s_setprio 0
	s_setprio 1
	s_waitcnt lgkmcnt(0)
	v_mfma_f32_16x16x32_bf16 v[116:119], v[152:155], v[176:179], v[116:119]
	v_mfma_f32_16x16x32_bf16 v[116:119], v[156:159], v[180:183], v[116:119]
	v_mfma_f32_16x16x32_bf16 v[100:103], v[152:155], v[184:187], v[100:103]
	v_mfma_f32_16x16x32_bf16 v[100:103], v[156:159], v[188:191], v[100:103]
	v_mfma_f32_16x16x32_bf16 v[84:87], v[152:155], v[192:195], v[84:87]
	v_mfma_f32_16x16x32_bf16 v[84:87], v[156:159], v[196:199], v[84:87]
	v_mfma_f32_16x16x32_bf16 v[68:71], v[152:155], v[200:203], v[68:71]
	v_mfma_f32_16x16x32_bf16 v[68:71], v[156:159], v[204:207], v[68:71]
	v_mfma_f32_16x16x32_bf16 v[64:67], v[168:171], v[200:203], v[64:67]
	v_mfma_f32_16x16x32_bf16 v[64:67], v[172:175], v[204:207], v[64:67]
	v_mfma_f32_16x16x32_bf16 v[80:83], v[168:171], v[192:195], v[80:83]
	v_mfma_f32_16x16x32_bf16 v[80:83], v[172:175], v[196:199], v[80:83]
	v_mfma_f32_16x16x32_bf16 v[96:99], v[168:171], v[184:187], v[96:99]
	v_mfma_f32_16x16x32_bf16 v[96:99], v[172:175], v[188:191], v[96:99]
	v_mfma_f32_16x16x32_bf16 v[112:115], v[168:171], v[176:179], v[112:115]
	v_mfma_f32_16x16x32_bf16 v[112:115], v[172:175], v[180:183], v[112:115]
	s_setprio 0
	s_barrier
	ds_read_b128 v[176:179], v164 offset:49152
	ds_read_b128 v[180:183], v164 offset:50176
	ds_read_b128 v[184:187], v164 offset:51200
	ds_read_b128 v[188:191], v164 offset:52224
	ds_read_b128 v[192:195], v164 offset:53248
	ds_read_b128 v[196:199], v164 offset:54272
	ds_read_b128 v[200:203], v164 offset:55296
	ds_read_b128 v[204:207], v164 offset:56320
	s_mov_b32 m0, s64
	s_nop 0
	global_load_lds_dwordx4 v160, s[52:53]
	s_add_u32 s52, s96, 0xa000
	s_addc_u32 s53, s97, 0
	s_mov_b32 m0, s65
	s_nop 0
	global_load_lds_dwordx4 v160, s[52:53]
	s_add_u32 s52, s96, 0xc000
	s_addc_u32 s53, s97, 0
	s_mov_b32 m0, s68
	s_nop 0
	global_load_lds_dwordx4 v160, s[52:53]
	s_add_u32 s52, s96, 0xe000
	s_addc_u32 s53, s97, 0
	s_mov_b32 m0, s69
	s_nop 0
	global_load_lds_dwordx4 v160, s[52:53]
	s_nop 0
	s_mov_b32 m0, s66
	s_nop 0
	global_load_lds_dwordx4 v160, s[2:3]
	s_add_u32 s2, s80, 0xa000
	s_addc_u32 s3, s81, 0
	s_mov_b32 m0, s67
	s_nop 0
	global_load_lds_dwordx4 v160, s[2:3]
	s_waitcnt vmcnt(8)
	s_waitcnt lgkmcnt(0)
	s_barrier
	s_setprio 1
	s_waitcnt lgkmcnt(7)
	s_waitcnt lgkmcnt(0)
	v_mfma_f32_16x16x32_bf16 v[60:63], v[128:131], v[176:179], v[60:63]
	v_mfma_f32_16x16x32_bf16 v[60:63], v[132:135], v[180:183], v[60:63]
	v_mfma_f32_16x16x32_bf16 v[44:47], v[128:131], v[184:187], v[44:47]
	v_mfma_f32_16x16x32_bf16 v[44:47], v[132:135], v[188:191], v[44:47]
	v_mfma_f32_16x16x32_bf16 v[28:31], v[128:131], v[192:195], v[28:31]
	v_mfma_f32_16x16x32_bf16 v[28:31], v[132:135], v[196:199], v[28:31]
	v_mfma_f32_16x16x32_bf16 v[12:15], v[128:131], v[200:203], v[12:15]
	v_mfma_f32_16x16x32_bf16 v[12:15], v[132:135], v[204:207], v[12:15]
	v_mfma_f32_16x16x32_bf16 v[8:11], v[136:139], v[200:203], v[8:11]
	v_mfma_f32_16x16x32_bf16 v[8:11], v[140:143], v[204:207], v[8:11]
	v_mfma_f32_16x16x32_bf16 v[24:27], v[136:139], v[192:195], v[24:27]
	v_mfma_f32_16x16x32_bf16 v[24:27], v[140:143], v[196:199], v[24:27]
	v_mfma_f32_16x16x32_bf16 v[40:43], v[136:139], v[184:187], v[40:43]
	v_mfma_f32_16x16x32_bf16 v[40:43], v[140:143], v[188:191], v[40:43]
	v_mfma_f32_16x16x32_bf16 v[56:59], v[136:139], v[176:179], v[56:59]
	v_mfma_f32_16x16x32_bf16 v[56:59], v[140:143], v[180:183], v[56:59]
	s_setprio 0
	s_setprio 1
	s_waitcnt lgkmcnt(0)
	v_mfma_f32_16x16x32_bf16 v[52:55], v[152:155], v[176:179], v[52:55]
	v_mfma_f32_16x16x32_bf16 v[52:55], v[156:159], v[180:183], v[52:55]
	v_mfma_f32_16x16x32_bf16 v[36:39], v[152:155], v[184:187], v[36:39]
	v_mfma_f32_16x16x32_bf16 v[36:39], v[156:159], v[188:191], v[36:39]
	v_mfma_f32_16x16x32_bf16 v[20:23], v[152:155], v[192:195], v[20:23]
	v_mfma_f32_16x16x32_bf16 v[20:23], v[156:159], v[196:199], v[20:23]
	v_mfma_f32_16x16x32_bf16 v[4:7], v[152:155], v[200:203], v[4:7]
	v_mfma_f32_16x16x32_bf16 v[4:7], v[156:159], v[204:207], v[4:7]
	v_mfma_f32_16x16x32_bf16 v[0:3], v[168:171], v[200:203], v[0:3]
	v_mfma_f32_16x16x32_bf16 v[0:3], v[172:175], v[204:207], v[0:3]
	v_mfma_f32_16x16x32_bf16 v[16:19], v[168:171], v[192:195], v[16:19]
	v_mfma_f32_16x16x32_bf16 v[16:19], v[172:175], v[196:199], v[16:19]
	v_mfma_f32_16x16x32_bf16 v[32:35], v[168:171], v[184:187], v[32:35]
	v_mfma_f32_16x16x32_bf16 v[32:35], v[172:175], v[188:191], v[32:35]
	v_mfma_f32_16x16x32_bf16 v[48:51], v[168:171], v[176:179], v[48:51]
	v_mfma_f32_16x16x32_bf16 v[48:51], v[172:175], v[180:183], v[48:51]
	s_setprio 0
	s_barrier
	s_add_i32 s79, s79, 2
	s_add_u32 s77, s77, 0x10000
	s_addc_u32 s78, s78, 0
	s_cmp_gt_u32 s79, 61
	s_mov_b64 s[52:53], s[48:49]
	s_cbranch_scc0 .LBB0_425
	s_and_b64 vcc, exec, s[14:15]
	s_cbranch_vccz .LBB0_428
	s_barrier

.LBB0_1402:
	s_add_u32 s44, s2, 0x10000
	s_waitcnt lgkmcnt(0)
	s_addc_u32 s45, s3, 0
	s_add_u32 s52, s56, 0x10000
	s_addc_u32 s53, s57, 0
	s_barrier
	s_setprio 1
	s_waitcnt lgkmcnt(7)
	s_waitcnt lgkmcnt(0)
	v_mfma_f32_16x16x32_bf16 v[32:35], v[16:19], v[68:71], 0
	v_mfma_f32_16x16x32_bf16 v[32:35], v[20:23], v[72:75], v[32:35]
	v_mfma_f32_16x16x32_bf16 v[40:43], v[16:19], v[84:87], 0
	v_mfma_f32_16x16x32_bf16 v[40:43], v[20:23], v[88:91], v[40:43]
	v_mfma_f32_16x16x32_bf16 v[48:51], v[16:19], v[92:95], 0
	v_mfma_f32_16x16x32_bf16 v[48:51], v[20:23], v[96:99], v[48:51]
	v_mfma_f32_16x16x32_bf16 v[56:59], v[16:19], v[76:79], 0
	v_mfma_f32_16x16x32_bf16 v[56:59], v[20:23], v[80:83], v[56:59]
	v_mfma_f32_16x16x32_bf16 v[60:63], v[24:27], v[76:79], 0
	v_mfma_f32_16x16x32_bf16 v[60:63], v[28:31], v[80:83], v[60:63]
	v_mfma_f32_16x16x32_bf16 v[52:55], v[24:27], v[92:95], 0
	v_mfma_f32_16x16x32_bf16 v[52:55], v[28:31], v[96:99], v[52:55]
	v_mfma_f32_16x16x32_bf16 v[44:47], v[24:27], v[84:87], 0
	v_mfma_f32_16x16x32_bf16 v[44:47], v[28:31], v[88:91], v[44:47]
	v_mfma_f32_16x16x32_bf16 v[36:39], v[24:27], v[68:71], 0
	v_mfma_f32_16x16x32_bf16 v[36:39], v[28:31], v[72:75], v[36:39]
	s_setprio 0
	s_setprio 1
	v_mfma_f32_16x16x32_bf16 v[64:67], v[0:3], v[68:71], 0
	v_mfma_f32_16x16x32_bf16 v[68:71], v[8:11], v[68:71], 0
	v_mfma_f32_16x16x32_bf16 v[64:67], v[4:7], v[72:75], v[64:67]
	v_mfma_f32_16x16x32_bf16 v[68:71], v[12:15], v[72:75], v[68:71]
	v_mfma_f32_16x16x32_bf16 v[72:75], v[0:3], v[84:87], 0
	v_mfma_f32_16x16x32_bf16 v[84:87], v[8:11], v[84:87], 0
	v_mfma_f32_16x16x32_bf16 v[72:75], v[4:7], v[88:91], v[72:75]
	v_mfma_f32_16x16x32_bf16 v[84:87], v[12:15], v[88:91], v[84:87]
	v_mfma_f32_16x16x32_bf16 v[88:91], v[0:3], v[92:95], 0
	v_mfma_f32_16x16x32_bf16 v[92:95], v[8:11], v[92:95], 0
	v_mfma_f32_16x16x32_bf16 v[88:91], v[4:7], v[96:99], v[88:91]
	v_mfma_f32_16x16x32_bf16 v[96:99], v[12:15], v[96:99], v[92:95]
	v_mfma_f32_16x16x32_bf16 v[92:95], v[0:3], v[76:79], 0
	v_mfma_f32_16x16x32_bf16 v[76:79], v[8:11], v[76:79], 0
	v_mfma_f32_16x16x32_bf16 v[108:111], v[4:7], v[80:83], v[92:95]
	v_mfma_f32_16x16x32_bf16 v[112:115], v[12:15], v[80:83], v[76:79]
	s_setprio 0
	s_barrier
	ds_read_b128 v[120:123], v214 offset:16384
	ds_read_b128 v[124:127], v214 offset:17408
	ds_read_b128 v[104:107], v214 offset:18432
	ds_read_b128 v[116:119], v214 offset:19456
	ds_read_b128 v[92:95], v214 offset:20480
	ds_read_b128 v[100:103], v214 offset:21504
	ds_read_b128 v[76:79], v214 offset:22528
	ds_read_b128 v[80:83], v214 offset:23552
	s_mov_b32 m0, s47
	s_nop 0
	global_load_lds_dwordx4 v210, s[52:53]
	s_add_u32 s52, s56, 0x12000
	s_addc_u32 s53, s57, 0
	s_mov_b32 m0, s49
	s_nop 0
	global_load_lds_dwordx4 v210, s[52:53]
	s_add_u32 s52, s56, 0x14000
	s_addc_u32 s53, s57, 0
	s_mov_b32 m0, s61
	s_nop 0
	global_load_lds_dwordx4 v210, s[52:53]
	s_add_u32 s52, s56, 0x16000
	s_addc_u32 s53, s57, 0
	s_mov_b32 m0, s62
	s_nop 0
	global_load_lds_dwordx4 v210, s[52:53]
	s_nop 0
	s_mov_b32 m0, s60
	s_nop 0
	global_load_lds_dwordx4 v210, s[44:45]
	s_add_u32 s44, s2, 0x12000
	s_addc_u32 s45, s3, 0
	s_mov_b32 m0, s63
	s_nop 0
	global_load_lds_dwordx4 v210, s[44:45]
	s_and_b64 vcc, exec, s[42:43]
	s_cbranch_vccz .LBB0_1429
	s_waitcnt vmcnt(24)
	s_cbranch_execnz .LBB0_1405

.LBB0_1406:
	ds_read_b128 v[72:75], v212
	ds_read_b128 v[84:87], v212 offset:1024
	ds_read_b128 v[96:99], v212 offset:2048
	ds_read_b128 v[108:111], v212 offset:3072
	ds_read_b128 v[112:115], v213
	ds_read_b128 v[136:139], v213 offset:1024
	ds_read_b128 v[148:151], v213 offset:2048
	ds_read_b128 v[160:163], v213 offset:3072
	s_cmp_eq_u32 s90, 60
	s_cselect_b32 s2, s82, s54
	s_cselect_b32 s3, s41, s55
	s_cselect_b32 s58, s83, s88
	s_cselect_b32 s59, s39, s89
	s_add_u32 s56, s2, 0x8000
	s_addc_u32 s57, s3, 0
	ds_read_b128 v[164:167], v214
	ds_read_b128 v[168:171], v214 offset:1024
	ds_read_b128 v[172:175], v214 offset:2048
	ds_read_b128 v[176:179], v214 offset:3072
	ds_read_b128 v[180:183], v214 offset:4096
	ds_read_b128 v[184:187], v214 offset:5120
	ds_read_b128 v[188:191], v214 offset:6144
	ds_read_b128 v[192:195], v214 offset:7168
	s_add_u32 s52, s54, 0xffffc000
	s_addc_u32 s53, s55, -1
	s_mov_b32 m0, s75
	s_nop 0
	global_load_lds_dwordx4 v210, s[52:53]
	s_add_u32 s52, s54, 0xffffe000
	s_addc_u32 s53, s55, -1
	s_mov_b32 m0, s78
	s_nop 0
	global_load_lds_dwordx4 v210, s[52:53]
	s_waitcnt vmcnt(8)
	s_waitcnt lgkmcnt(0)
	s_add_u32 s52, s58, 0x8000
	s_addc_u32 s53, s59, 0
	s_barrier
	s_setprio 1
	s_waitcnt lgkmcnt(7)
	v_mfma_f32_16x16x32_bf16 v[156:159], v[72:75], v[164:167], v[156:159]
	v_mfma_f32_16x16x32_bf16 v[152:155], v[96:99], v[164:167], v[152:155]
	s_waitcnt lgkmcnt(5)
	v_mfma_f32_16x16x32_bf16 v[132:135], v[72:75], v[172:175], v[132:135]
	v_mfma_f32_16x16x32_bf16 v[126:129], v[96:99], v[172:175], v[128:131]
	s_waitcnt lgkmcnt(3)
	v_mfma_f32_16x16x32_bf16 v[104:107], v[72:75], v[180:183], v[104:107]
	v_mfma_f32_16x16x32_bf16 v[100:103], v[96:99], v[180:183], v[100:103]
	s_waitcnt lgkmcnt(1)
	v_mfma_f32_16x16x32_bf16 v[80:83], v[72:75], v[188:191], v[80:83]
	v_mfma_f32_16x16x32_bf16 v[76:79], v[96:99], v[188:191], v[76:79]
	v_mfma_f32_16x16x32_bf16 v[156:159], v[84:87], v[168:171], v[156:159]
	v_mfma_f32_16x16x32_bf16 v[152:155], v[108:111], v[168:171], v[152:155]
	v_mfma_f32_16x16x32_bf16 v[132:135], v[84:87], v[176:179], v[132:135]
	v_mfma_f32_16x16x32_bf16 v[126:129], v[108:111], v[176:179], v[126:129]
	v_mfma_f32_16x16x32_bf16 v[104:107], v[84:87], v[184:187], v[104:107]
	v_mfma_f32_16x16x32_bf16 v[100:103], v[108:111], v[184:187], v[100:103]
	s_waitcnt lgkmcnt(0)
	v_mfma_f32_16x16x32_bf16 v[80:83], v[84:87], v[192:195], v[80:83]
	v_mfma_f32_16x16x32_bf16 v[76:79], v[108:111], v[192:195], v[76:79]
	s_setprio 0
	s_setprio 1
	s_waitcnt lgkmcnt(0)
	v_mfma_f32_16x16x32_bf16 v[144:147], v[112:115], v[164:167], v[144:147]
	v_mfma_f32_16x16x32_bf16 v[144:147], v[136:139], v[168:171], v[144:147]
	v_mfma_f32_16x16x32_bf16 v[120:123], v[112:115], v[172:175], v[120:123]
	v_mfma_f32_16x16x32_bf16 v[120:123], v[136:139], v[176:179], v[120:123]
	v_mfma_f32_16x16x32_bf16 v[92:95], v[112:115], v[180:183], v[92:95]
	v_mfma_f32_16x16x32_bf16 v[92:95], v[136:139], v[184:187], v[92:95]
	v_mfma_f32_16x16x32_bf16 v[68:71], v[112:115], v[188:191], v[68:71]
	v_mfma_f32_16x16x32_bf16 v[68:71], v[136:139], v[192:195], v[68:71]
	v_mfma_f32_16x16x32_bf16 v[64:67], v[148:151], v[188:191], v[64:67]
	v_mfma_f32_16x16x32_bf16 v[64:67], v[160:163], v[192:195], v[64:67]
	v_mfma_f32_16x16x32_bf16 v[88:91], v[148:151], v[180:183], v[88:91]
	v_mfma_f32_16x16x32_bf16 v[88:91], v[160:163], v[184:187], v[88:91]
	v_mfma_f32_16x16x32_bf16 v[116:119], v[148:151], v[172:175], v[116:119]
	v_mfma_f32_16x16x32_bf16 v[116:119], v[160:163], v[176:179], v[116:119]
	v_mfma_f32_16x16x32_bf16 v[140:143], v[148:151], v[164:167], v[140:143]
	v_mfma_f32_16x16x32_bf16 v[140:143], v[160:163], v[168:171], v[140:143]
	s_setprio 0
	s_barrier
	s_add_u32 s92, s58, 0x2000
	ds_read_b128 v[164:167], v214 offset:16384
	ds_read_b128 v[168:171], v214 offset:17408
	ds_read_b128 v[172:175], v214 offset:18432
	ds_read_b128 v[176:179], v214 offset:19456
	ds_read_b128 v[180:183], v214 offset:20480
	ds_read_b128 v[184:187], v214 offset:21504
	ds_read_b128 v[188:191], v214 offset:22528
	ds_read_b128 v[192:195], v214 offset:23552
	s_mov_b32 m0, s47
	s_nop 0
	global_load_lds_dwordx4 v210, s[58:59]
	s_addc_u32 s93, s59, 0
	s_mov_b32 m0, s49
	s_nop 0
	global_load_lds_dwordx4 v210, s[92:93]
	s_add_u32 s92, s58, 0x4000
	s_addc_u32 s93, s59, 0
	s_mov_b32 m0, s61
	s_nop 0
	global_load_lds_dwordx4 v210, s[92:93]
	s_add_u32 s92, s58, 0x6000
	s_addc_u32 s93, s59, 0
	s_mov_b32 m0, s62
	s_nop 0
	global_load_lds_dwordx4 v210, s[92:93]
	s_add_u32 s92, s2, 0x2000
	s_mov_b32 m0, s60
	s_nop 0
	global_load_lds_dwordx4 v210, s[2:3]
	s_addc_u32 s93, s3, 0
	s_mov_b32 m0, s63
	s_nop 0
	global_load_lds_dwordx4 v210, s[92:93]
	s_waitcnt vmcnt(8)
	s_waitcnt lgkmcnt(0)
	s_barrier
	s_setprio 1
	s_waitcnt lgkmcnt(7)
	s_waitcnt lgkmcnt(0)
	v_mfma_f32_16x16x32_bf16 v[60:63], v[72:75], v[164:167], v[60:63]
	v_mfma_f32_16x16x32_bf16 v[60:63], v[84:87], v[168:171], v[60:63]
	v_mfma_f32_16x16x32_bf16 v[44:47], v[72:75], v[172:175], v[44:47]
	v_mfma_f32_16x16x32_bf16 v[44:47], v[84:87], v[176:179], v[44:47]
	v_mfma_f32_16x16x32_bf16 v[28:31], v[72:75], v[180:183], v[28:31]
	v_mfma_f32_16x16x32_bf16 v[28:31], v[84:87], v[184:187], v[28:31]
	v_mfma_f32_16x16x32_bf16 v[12:15], v[72:75], v[188:191], v[12:15]
	v_mfma_f32_16x16x32_bf16 v[12:15], v[84:87], v[192:195], v[12:15]
	v_mfma_f32_16x16x32_bf16 v[8:11], v[96:99], v[188:191], v[8:11]
	v_mfma_f32_16x16x32_bf16 v[8:11], v[108:111], v[192:195], v[8:11]
	v_mfma_f32_16x16x32_bf16 v[24:27], v[96:99], v[180:183], v[24:27]
	v_mfma_f32_16x16x32_bf16 v[24:27], v[108:111], v[184:187], v[24:27]
	v_mfma_f32_16x16x32_bf16 v[40:43], v[96:99], v[172:175], v[40:43]
	v_mfma_f32_16x16x32_bf16 v[40:43], v[108:111], v[176:179], v[40:43]
	v_mfma_f32_16x16x32_bf16 v[56:59], v[96:99], v[164:167], v[56:59]
	v_mfma_f32_16x16x32_bf16 v[56:59], v[108:111], v[168:171], v[56:59]
	s_setprio 0
	s_setprio 1
	s_waitcnt lgkmcnt(0)
	v_mfma_f32_16x16x32_bf16 v[52:55], v[112:115], v[164:167], v[52:55]
	v_mfma_f32_16x16x32_bf16 v[52:55], v[136:139], v[168:171], v[52:55]
	v_mfma_f32_16x16x32_bf16 v[36:39], v[112:115], v[172:175], v[36:39]
	v_mfma_f32_16x16x32_bf16 v[36:39], v[136:139], v[176:179], v[36:39]
	v_mfma_f32_16x16x32_bf16 v[20:23], v[112:115], v[180:183], v[20:23]
	v_mfma_f32_16x16x32_bf16 v[20:23], v[136:139], v[184:187], v[20:23]
	v_mfma_f32_16x16x32_bf16 v[4:7], v[112:115], v[188:191], v[4:7]
	v_mfma_f32_16x16x32_bf16 v[4:7], v[136:139], v[192:195], v[4:7]
	v_mfma_f32_16x16x32_bf16 v[0:3], v[148:151], v[188:191], v[0:3]
	v_mfma_f32_16x16x32_bf16 v[0:3], v[160:163], v[192:195], v[0:3]
	v_mfma_f32_16x16x32_bf16 v[16:19], v[148:151], v[180:183], v[16:19]
	v_mfma_f32_16x16x32_bf16 v[16:19], v[160:163], v[184:187], v[16:19]
	v_mfma_f32_16x16x32_bf16 v[32:35], v[148:151], v[172:175], v[32:35]
	v_mfma_f32_16x16x32_bf16 v[32:35], v[160:163], v[176:179], v[32:35]
	v_mfma_f32_16x16x32_bf16 v[48:51], v[148:151], v[164:167], v[48:51]
	v_mfma_f32_16x16x32_bf16 v[48:51], v[160:163], v[168:171], v[48:51]
	s_setprio 0
	s_barrier
	ds_read_b128 v[72:75], v124
	ds_read_b128 v[84:87], v124 offset:1024
	ds_read_b128 v[96:99], v124 offset:2048
	ds_read_b128 v[108:111], v124 offset:3072
	ds_read_b128 v[112:115], v125
	ds_read_b128 v[136:139], v125 offset:1024
	ds_read_b128 v[148:151], v125 offset:2048
	ds_read_b128 v[160:163], v125 offset:3072
	ds_read_b128 v[164:167], v214 offset:32768
	ds_read_b128 v[168:171], v214 offset:33792
	ds_read_b128 v[172:175], v214 offset:34816
	ds_read_b128 v[176:179], v214 offset:35840
	ds_read_b128 v[180:183], v214 offset:36864
	ds_read_b128 v[184:187], v214 offset:37888
	ds_read_b128 v[188:191], v214 offset:38912
	ds_read_b128 v[192:195], v214 offset:39936
	s_add_u32 s92, s2, 0x4000
	s_addc_u32 s93, s3, 0
	s_mov_b32 m0, s64
	s_nop 0
	global_load_lds_dwordx4 v210, s[92:93]
	s_add_u32 s92, s2, 0x6000
	s_addc_u32 s93, s3, 0
	s_mov_b32 m0, s65
	s_nop 0
	global_load_lds_dwordx4 v210, s[92:93]
	s_waitcnt vmcnt(8)
	s_waitcnt lgkmcnt(0)
	s_barrier
	s_setprio 1
	s_waitcnt lgkmcnt(7)
	v_mfma_f32_16x16x32_bf16 v[156:159], v[72:75], v[164:167], v[156:159]
	v_mfma_f32_16x16x32_bf16 v[152:155], v[96:99], v[164:167], v[152:155]
	s_waitcnt lgkmcnt(5)
	v_mfma_f32_16x16x32_bf16 v[130:133], v[72:75], v[172:175], v[132:135]
	v_mfma_f32_16x16x32_bf16 v[126:129], v[96:99], v[172:175], v[126:129]
	s_waitcnt lgkmcnt(3)
	v_mfma_f32_16x16x32_bf16 v[104:107], v[72:75], v[180:183], v[104:107]
	v_mfma_f32_16x16x32_bf16 v[100:103], v[96:99], v[180:183], v[100:103]
	s_waitcnt lgkmcnt(1)
	v_mfma_f32_16x16x32_bf16 v[80:83], v[72:75], v[188:191], v[80:83]
	v_mfma_f32_16x16x32_bf16 v[76:79], v[96:99], v[188:191], v[76:79]
	v_mfma_f32_16x16x32_bf16 v[156:159], v[84:87], v[168:171], v[156:159]
	v_mfma_f32_16x16x32_bf16 v[152:155], v[108:111], v[168:171], v[152:155]
	v_mfma_f32_16x16x32_bf16 v[132:135], v[84:87], v[176:179], v[130:133]
	v_mfma_f32_16x16x32_bf16 v[128:131], v[108:111], v[176:179], v[126:129]
	v_mfma_f32_16x16x32_bf16 v[104:107], v[84:87], v[184:187], v[104:107]
	v_mfma_f32_16x16x32_bf16 v[100:103], v[108:111], v[184:187], v[100:103]
	s_waitcnt lgkmcnt(0)
	v_mfma_f32_16x16x32_bf16 v[80:83], v[84:87], v[192:195], v[80:83]
	v_mfma_f32_16x16x32_bf16 v[76:79], v[108:111], v[192:195], v[76:79]
	s_setprio 0
	s_setprio 1
	s_waitcnt lgkmcnt(0)
	v_mfma_f32_16x16x32_bf16 v[144:147], v[112:115], v[164:167], v[144:147]
	v_mfma_f32_16x16x32_bf16 v[144:147], v[136:139], v[168:171], v[144:147]
	v_mfma_f32_16x16x32_bf16 v[120:123], v[112:115], v[172:175], v[120:123]
	v_mfma_f32_16x16x32_bf16 v[120:123], v[136:139], v[176:179], v[120:123]
	v_mfma_f32_16x16x32_bf16 v[92:95], v[112:115], v[180:183], v[92:95]
	v_mfma_f32_16x16x32_bf16 v[92:95], v[136:139], v[184:187], v[92:95]
	v_mfma_f32_16x16x32_bf16 v[68:71], v[112:115], v[188:191], v[68:71]
	v_mfma_f32_16x16x32_bf16 v[68:71], v[136:139], v[192:195], v[68:71]
	v_mfma_f32_16x16x32_bf16 v[64:67], v[148:151], v[188:191], v[64:67]
	v_mfma_f32_16x16x32_bf16 v[64:67], v[160:163], v[192:195], v[64:67]
	v_mfma_f32_16x16x32_bf16 v[88:91], v[148:151], v[180:183], v[88:91]
	v_mfma_f32_16x16x32_bf16 v[88:91], v[160:163], v[184:187], v[88:91]
	v_mfma_f32_16x16x32_bf16 v[116:119], v[148:151], v[172:175], v[116:119]
	v_mfma_f32_16x16x32_bf16 v[116:119], v[160:163], v[176:179], v[116:119]
	v_mfma_f32_16x16x32_bf16 v[140:143], v[148:151], v[164:167], v[140:143]
	v_mfma_f32_16x16x32_bf16 v[140:143], v[160:163], v[168:171], v[140:143]
	s_setprio 0
	s_barrier
	ds_read_b128 v[164:167], v214 offset:49152
	ds_read_b128 v[168:171], v214 offset:50176
	ds_read_b128 v[172:175], v214 offset:51200
	ds_read_b128 v[176:179], v214 offset:52224
	ds_read_b128 v[180:183], v214 offset:53248
	ds_read_b128 v[184:187], v214 offset:54272
	ds_read_b128 v[188:191], v214 offset:55296
	ds_read_b128 v[192:195], v214 offset:56320
	s_mov_b32 m0, s69
	s_nop 0
	global_load_lds_dwordx4 v210, s[52:53]
	s_add_u32 s52, s58, 0xa000
	s_addc_u32 s53, s59, 0
	s_mov_b32 m0, s70
	s_nop 0
	global_load_lds_dwordx4 v210, s[52:53]
	s_add_u32 s52, s58, 0xc000
	s_addc_u32 s53, s59, 0
	s_mov_b32 m0, s73
	s_nop 0
	global_load_lds_dwordx4 v210, s[52:53]
	s_add_u32 s52, s58, 0xe000
	s_addc_u32 s53, s59, 0
	s_mov_b32 m0, s74
	s_nop 0
	global_load_lds_dwordx4 v210, s[52:53]
	s_add_u32 s2, s2, 0xa000
	s_mov_b32 m0, s71
	s_nop 0
	global_load_lds_dwordx4 v210, s[56:57]
	s_addc_u32 s3, s3, 0
	s_mov_b32 m0, s72
	s_nop 0
	global_load_lds_dwordx4 v210, s[2:3]
	s_waitcnt vmcnt(8)
	s_waitcnt lgkmcnt(0)
	s_barrier
	s_setprio 1
	s_waitcnt lgkmcnt(7)
	s_waitcnt lgkmcnt(0)
	v_mfma_f32_16x16x32_bf16 v[60:63], v[72:75], v[164:167], v[60:63]
	v_mfma_f32_16x16x32_bf16 v[60:63], v[84:87], v[168:171], v[60:63]
	v_mfma_f32_16x16x32_bf16 v[44:47], v[72:75], v[172:175], v[44:47]
	v_mfma_f32_16x16x32_bf16 v[44:47], v[84:87], v[176:179], v[44:47]
	v_mfma_f32_16x16x32_bf16 v[28:31], v[72:75], v[180:183], v[28:31]
	v_mfma_f32_16x16x32_bf16 v[28:31], v[84:87], v[184:187], v[28:31]
	v_mfma_f32_16x16x32_bf16 v[12:15], v[72:75], v[188:191], v[12:15]
	v_mfma_f32_16x16x32_bf16 v[12:15], v[84:87], v[192:195], v[12:15]
	v_mfma_f32_16x16x32_bf16 v[8:11], v[96:99], v[188:191], v[8:11]
	v_mfma_f32_16x16x32_bf16 v[8:11], v[108:111], v[192:195], v[8:11]
	v_mfma_f32_16x16x32_bf16 v[24:27], v[96:99], v[180:183], v[24:27]
	v_mfma_f32_16x16x32_bf16 v[24:27], v[108:111], v[184:187], v[24:27]
	v_mfma_f32_16x16x32_bf16 v[40:43], v[96:99], v[172:175], v[40:43]
	v_mfma_f32_16x16x32_bf16 v[40:43], v[108:111], v[176:179], v[40:43]
	v_mfma_f32_16x16x32_bf16 v[56:59], v[96:99], v[164:167], v[56:59]
	v_mfma_f32_16x16x32_bf16 v[56:59], v[108:111], v[168:171], v[56:59]
	s_setprio 0
	s_setprio 1
	s_waitcnt lgkmcnt(0)
	v_mfma_f32_16x16x32_bf16 v[52:55], v[112:115], v[164:167], v[52:55]
	v_mfma_f32_16x16x32_bf16 v[52:55], v[136:139], v[168:171], v[52:55]
	v_mfma_f32_16x16x32_bf16 v[36:39], v[112:115], v[172:175], v[36:39]
	v_mfma_f32_16x16x32_bf16 v[36:39], v[136:139], v[176:179], v[36:39]
	v_mfma_f32_16x16x32_bf16 v[20:23], v[112:115], v[180:183], v[20:23]
	v_mfma_f32_16x16x32_bf16 v[20:23], v[136:139], v[184:187], v[20:23]
	v_mfma_f32_16x16x32_bf16 v[4:7], v[112:115], v[188:191], v[4:7]
	v_mfma_f32_16x16x32_bf16 v[4:7], v[136:139], v[192:195], v[4:7]
	v_mfma_f32_16x16x32_bf16 v[0:3], v[148:151], v[188:191], v[0:3]
	v_mfma_f32_16x16x32_bf16 v[0:3], v[160:163], v[192:195], v[0:3]
	v_mfma_f32_16x16x32_bf16 v[16:19], v[148:151], v[180:183], v[16:19]
	v_mfma_f32_16x16x32_bf16 v[16:19], v[160:163], v[184:187], v[16:19]
	v_mfma_f32_16x16x32_bf16 v[32:35], v[148:151], v[172:175], v[32:35]
	v_mfma_f32_16x16x32_bf16 v[32:35], v[160:163], v[176:179], v[32:35]
	v_mfma_f32_16x16x32_bf16 v[48:51], v[148:151], v[164:167], v[48:51]
	v_mfma_f32_16x16x32_bf16 v[48:51], v[160:163], v[168:171], v[48:51]
	s_setprio 0
	s_barrier
	s_add_i32 s90, s90, 2
	s_add_u32 s54, s54, 0x10000
	s_addc_u32 s55, s55, 0
	s_add_u32 s88, s88, 0x10000
	s_addc_u32 s89, s89, 0
	s_cmp_gt_u32 s90, 61
	s_cbranch_scc0 .LBB0_1406
	s_and_b64 vcc, exec, s[12:13]
	s_cbranch_vccz .LBB0_1409
	s_barrier

.LBB0_1501:
	s_add_u32 s48, s2, 0x10000
	s_waitcnt lgkmcnt(0)
	s_addc_u32 s49, s3, 0
	s_add_u32 s52, s58, 0x10000
	s_addc_u32 s53, s59, 0
	s_barrier
	s_setprio 1
	s_waitcnt lgkmcnt(7)
	s_waitcnt lgkmcnt(0)
	v_mfma_f32_16x16x32_bf16 v[32:35], v[16:19], v[68:71], 0
	v_mfma_f32_16x16x32_bf16 v[32:35], v[20:23], v[80:83], v[32:35]
	v_mfma_f32_16x16x32_bf16 v[40:43], v[16:19], v[84:87], 0
	v_mfma_f32_16x16x32_bf16 v[40:43], v[20:23], v[96:99], v[40:43]
	v_mfma_f32_16x16x32_bf16 v[48:51], v[16:19], v[88:91], 0
	v_mfma_f32_16x16x32_bf16 v[48:51], v[20:23], v[92:95], v[48:51]
	v_mfma_f32_16x16x32_bf16 v[56:59], v[16:19], v[72:75], 0
	v_mfma_f32_16x16x32_bf16 v[56:59], v[20:23], v[76:79], v[56:59]
	v_mfma_f32_16x16x32_bf16 v[60:63], v[24:27], v[72:75], 0
	v_mfma_f32_16x16x32_bf16 v[60:63], v[28:31], v[76:79], v[60:63]
	v_mfma_f32_16x16x32_bf16 v[52:55], v[24:27], v[88:91], 0
	v_mfma_f32_16x16x32_bf16 v[52:55], v[28:31], v[92:95], v[52:55]
	v_mfma_f32_16x16x32_bf16 v[44:47], v[24:27], v[84:87], 0
	v_mfma_f32_16x16x32_bf16 v[44:47], v[28:31], v[96:99], v[44:47]
	v_mfma_f32_16x16x32_bf16 v[36:39], v[24:27], v[68:71], 0
	v_mfma_f32_16x16x32_bf16 v[36:39], v[28:31], v[80:83], v[36:39]
	s_setprio 0
	s_setprio 1
	v_mfma_f32_16x16x32_bf16 v[64:67], v[0:3], v[68:71], 0
	v_mfma_f32_16x16x32_bf16 v[68:71], v[8:11], v[68:71], 0
	v_mfma_f32_16x16x32_bf16 v[64:67], v[4:7], v[80:83], v[64:67]
	v_mfma_f32_16x16x32_bf16 v[68:71], v[12:15], v[80:83], v[68:71]
	v_mfma_f32_16x16x32_bf16 v[80:83], v[0:3], v[84:87], 0
	v_mfma_f32_16x16x32_bf16 v[84:87], v[8:11], v[84:87], 0
	v_mfma_f32_16x16x32_bf16 v[80:83], v[4:7], v[96:99], v[80:83]
	v_mfma_f32_16x16x32_bf16 v[84:87], v[12:15], v[96:99], v[84:87]
	v_mfma_f32_16x16x32_bf16 v[96:99], v[0:3], v[88:91], 0
	v_mfma_f32_16x16x32_bf16 v[88:91], v[8:11], v[88:91], 0
	v_mfma_f32_16x16x32_bf16 v[132:135], v[12:15], v[92:95], v[88:91]
	v_mfma_f32_16x16x32_bf16 v[88:91], v[0:3], v[72:75], 0
	v_mfma_f32_16x16x32_bf16 v[72:75], v[8:11], v[72:75], 0
	v_mfma_f32_16x16x32_bf16 v[128:131], v[4:7], v[92:95], v[96:99]
	v_mfma_f32_16x16x32_bf16 v[136:139], v[4:7], v[76:79], v[88:91]
	v_mfma_f32_16x16x32_bf16 v[140:143], v[12:15], v[76:79], v[72:75]
	s_setprio 0
	s_barrier
	ds_read_b128 v[104:107], v158 offset:16384
	ds_read_b128 v[108:111], v158 offset:17408
	ds_read_b128 v[96:99], v158 offset:18432
	ds_read_b128 v[100:103], v158 offset:19456
	ds_read_b128 v[88:91], v158 offset:20480
	ds_read_b128 v[92:95], v158 offset:21504
	ds_read_b128 v[72:75], v158 offset:22528
	ds_read_b128 v[76:79], v158 offset:23552
	s_mov_b32 m0, s57
	s_nop 0
	global_load_lds_dwordx4 v154, s[52:53]
	s_add_u32 s52, s58, 0x12000
	s_addc_u32 s53, s59, 0
	s_mov_b32 m0, s67
	s_nop 0
	global_load_lds_dwordx4 v154, s[52:53]
	s_add_u32 s52, s58, 0x14000
	s_addc_u32 s53, s59, 0
	s_mov_b32 m0, s68
	s_nop 0
	global_load_lds_dwordx4 v154, s[52:53]
	s_add_u32 s52, s58, 0x16000
	s_addc_u32 s53, s59, 0
	s_mov_b32 m0, s69
	s_nop 0
	global_load_lds_dwordx4 v154, s[52:53]
	s_nop 0
	s_mov_b32 m0, s66
	s_nop 0
	global_load_lds_dwordx4 v154, s[48:49]
	s_add_u32 s48, s2, 0x12000
	s_addc_u32 s49, s3, 0
	s_mov_b32 m0, s70
	s_nop 0
	global_load_lds_dwordx4 v154, s[48:49]
	s_and_b64 vcc, exec, s[46:47]
	s_cbranch_vccz .LBB0_1512
	s_waitcnt vmcnt(24)
	s_cbranch_execnz .LBB0_1504

.LBB0_1505:
	ds_read_b128 v[128:131], v156
	ds_read_b128 v[132:135], v156 offset:1024
	ds_read_b128 v[136:139], v156 offset:2048
	ds_read_b128 v[140:143], v156 offset:3072
	ds_read_b128 v[146:149], v157
	ds_read_b128 v[162:165], v157 offset:1024
	ds_read_b128 v[166:169], v157 offset:2048
	ds_read_b128 v[170:173], v157 offset:3072
	s_add_u32 s2, s52, 0x10000
	s_addc_u32 s3, s53, 0
	s_cmp_eq_u32 s96, 60
	s_cselect_b32 s58, s92, s2
	s_cselect_b32 s59, s45, s3
	s_cselect_b32 s64, s93, s54
	s_cselect_b32 s65, s43, s55
	s_add_u32 s60, s58, 0x8000
	s_addc_u32 s61, s59, 0
	ds_read_b128 v[174:177], v158
	ds_read_b128 v[178:181], v158 offset:1024
	ds_read_b128 v[182:185], v158 offset:2048
	ds_read_b128 v[186:189], v158 offset:3072
	ds_read_b128 v[190:193], v158 offset:4096
	ds_read_b128 v[194:197], v158 offset:5120
	ds_read_b128 v[198:201], v158 offset:6144
	ds_read_b128 v[202:205], v158 offset:7168
	s_add_u32 s12, s52, 0xc000
	s_addc_u32 s13, s53, 0
	s_mov_b32 m0, s81
	s_nop 0
	global_load_lds_dwordx4 v154, s[12:13]
	s_add_u32 s12, s52, 0xe000
	s_addc_u32 s13, s53, 0
	s_mov_b32 m0, s82
	s_nop 0
	global_load_lds_dwordx4 v154, s[12:13]
	s_waitcnt vmcnt(8)
	s_waitcnt lgkmcnt(0)
	s_add_u32 s52, s64, 0x8000
	s_addc_u32 s53, s65, 0
	s_barrier
	s_setprio 1
	s_waitcnt lgkmcnt(7)
	s_waitcnt lgkmcnt(0)
	v_mfma_f32_16x16x32_bf16 v[116:119], v[128:131], v[174:177], v[116:119]
	v_mfma_f32_16x16x32_bf16 v[116:119], v[132:135], v[178:181], v[116:119]
	v_mfma_f32_16x16x32_bf16 v[100:103], v[128:131], v[182:185], v[100:103]
	v_mfma_f32_16x16x32_bf16 v[100:103], v[132:135], v[186:189], v[100:103]
	v_mfma_f32_16x16x32_bf16 v[92:95], v[128:131], v[190:193], v[92:95]
	v_mfma_f32_16x16x32_bf16 v[92:95], v[132:135], v[194:197], v[92:95]
	v_mfma_f32_16x16x32_bf16 v[76:79], v[128:131], v[198:201], v[76:79]
	v_mfma_f32_16x16x32_bf16 v[76:79], v[132:135], v[202:205], v[76:79]
	v_mfma_f32_16x16x32_bf16 v[72:75], v[136:139], v[198:201], v[72:75]
	v_mfma_f32_16x16x32_bf16 v[72:75], v[140:143], v[202:205], v[72:75]
	v_mfma_f32_16x16x32_bf16 v[88:91], v[136:139], v[190:193], v[88:91]
	v_mfma_f32_16x16x32_bf16 v[88:91], v[140:143], v[194:197], v[88:91]
	v_mfma_f32_16x16x32_bf16 v[96:99], v[136:139], v[182:185], v[96:99]
	v_mfma_f32_16x16x32_bf16 v[96:99], v[140:143], v[186:189], v[96:99]
	v_mfma_f32_16x16x32_bf16 v[112:115], v[136:139], v[174:177], v[112:115]
	v_mfma_f32_16x16x32_bf16 v[112:115], v[140:143], v[178:181], v[112:115]
	s_setprio 0
	s_setprio 1
	s_waitcnt lgkmcnt(0)
	v_mfma_f32_16x16x32_bf16 v[124:127], v[146:149], v[174:177], v[124:127]
	v_mfma_f32_16x16x32_bf16 v[124:127], v[162:165], v[178:181], v[124:127]
	v_mfma_f32_16x16x32_bf16 v[108:111], v[146:149], v[182:185], v[108:111]
	v_mfma_f32_16x16x32_bf16 v[108:111], v[162:165], v[186:189], v[108:111]
	v_mfma_f32_16x16x32_bf16 v[84:87], v[146:149], v[190:193], v[84:87]
	v_mfma_f32_16x16x32_bf16 v[84:87], v[162:165], v[194:197], v[84:87]
	v_mfma_f32_16x16x32_bf16 v[68:71], v[146:149], v[198:201], v[68:71]
	v_mfma_f32_16x16x32_bf16 v[68:71], v[162:165], v[202:205], v[68:71]
	v_mfma_f32_16x16x32_bf16 v[64:67], v[166:169], v[198:201], v[64:67]
	v_mfma_f32_16x16x32_bf16 v[64:67], v[170:173], v[202:205], v[64:67]
	v_mfma_f32_16x16x32_bf16 v[80:83], v[166:169], v[190:193], v[80:83]
	v_mfma_f32_16x16x32_bf16 v[80:83], v[170:173], v[194:197], v[80:83]
	v_mfma_f32_16x16x32_bf16 v[104:107], v[166:169], v[182:185], v[104:107]
	v_mfma_f32_16x16x32_bf16 v[104:107], v[170:173], v[186:189], v[104:107]
	v_mfma_f32_16x16x32_bf16 v[120:123], v[166:169], v[174:177], v[120:123]
	v_mfma_f32_16x16x32_bf16 v[120:123], v[170:173], v[178:181], v[120:123]
	s_setprio 0
	s_barrier
	s_add_u32 s12, s64, 0x2000
	ds_read_b128 v[174:177], v158 offset:16384
	ds_read_b128 v[178:181], v158 offset:17408
	ds_read_b128 v[182:185], v158 offset:18432
	ds_read_b128 v[186:189], v158 offset:19456
	ds_read_b128 v[190:193], v158 offset:20480
	ds_read_b128 v[194:197], v158 offset:21504
	ds_read_b128 v[198:201], v158 offset:22528
	ds_read_b128 v[202:205], v158 offset:23552
	s_mov_b32 m0, s57
	s_nop 0
	global_load_lds_dwordx4 v154, s[64:65]
	s_addc_u32 s13, s65, 0
	s_mov_b32 m0, s67
	s_nop 0
	global_load_lds_dwordx4 v154, s[12:13]
	s_add_u32 s12, s64, 0x4000
	s_addc_u32 s13, s65, 0
	s_mov_b32 m0, s68
	s_nop 0
	global_load_lds_dwordx4 v154, s[12:13]
	s_add_u32 s12, s64, 0x6000
	s_addc_u32 s13, s65, 0
	s_mov_b32 m0, s69
	s_nop 0
	global_load_lds_dwordx4 v154, s[12:13]
	s_add_u32 s12, s58, 0x2000
	s_mov_b32 m0, s66
	s_nop 0
	global_load_lds_dwordx4 v154, s[58:59]
	s_addc_u32 s13, s59, 0
	s_mov_b32 m0, s70
	s_nop 0
	global_load_lds_dwordx4 v154, s[12:13]
	s_waitcnt vmcnt(8)
	s_waitcnt lgkmcnt(0)
	s_barrier
	s_setprio 1
	s_waitcnt lgkmcnt(7)
	s_waitcnt lgkmcnt(0)
	v_mfma_f32_16x16x32_bf16 v[60:63], v[128:131], v[174:177], v[60:63]
	v_mfma_f32_16x16x32_bf16 v[60:63], v[132:135], v[178:181], v[60:63]
	v_mfma_f32_16x16x32_bf16 v[44:47], v[128:131], v[182:185], v[44:47]
	v_mfma_f32_16x16x32_bf16 v[44:47], v[132:135], v[186:189], v[44:47]
	v_mfma_f32_16x16x32_bf16 v[28:31], v[128:131], v[190:193], v[28:31]
	v_mfma_f32_16x16x32_bf16 v[28:31], v[132:135], v[194:197], v[28:31]
	v_mfma_f32_16x16x32_bf16 v[12:15], v[128:131], v[198:201], v[12:15]
	v_mfma_f32_16x16x32_bf16 v[12:15], v[132:135], v[202:205], v[12:15]
	v_mfma_f32_16x16x32_bf16 v[8:11], v[136:139], v[198:201], v[8:11]
	v_mfma_f32_16x16x32_bf16 v[8:11], v[140:143], v[202:205], v[8:11]
	v_mfma_f32_16x16x32_bf16 v[24:27], v[136:139], v[190:193], v[24:27]
	v_mfma_f32_16x16x32_bf16 v[24:27], v[140:143], v[194:197], v[24:27]
	v_mfma_f32_16x16x32_bf16 v[40:43], v[136:139], v[182:185], v[40:43]
	v_mfma_f32_16x16x32_bf16 v[40:43], v[140:143], v[186:189], v[40:43]
	v_mfma_f32_16x16x32_bf16 v[56:59], v[136:139], v[174:177], v[56:59]
	v_mfma_f32_16x16x32_bf16 v[56:59], v[140:143], v[178:181], v[56:59]
	s_setprio 0
	s_setprio 1
	s_waitcnt lgkmcnt(0)
	v_mfma_f32_16x16x32_bf16 v[52:55], v[146:149], v[174:177], v[52:55]
	v_mfma_f32_16x16x32_bf16 v[52:55], v[162:165], v[178:181], v[52:55]
	v_mfma_f32_16x16x32_bf16 v[36:39], v[146:149], v[182:185], v[36:39]
	v_mfma_f32_16x16x32_bf16 v[36:39], v[162:165], v[186:189], v[36:39]
	v_mfma_f32_16x16x32_bf16 v[20:23], v[146:149], v[190:193], v[20:23]
	v_mfma_f32_16x16x32_bf16 v[20:23], v[162:165], v[194:197], v[20:23]
	v_mfma_f32_16x16x32_bf16 v[4:7], v[146:149], v[198:201], v[4:7]
	v_mfma_f32_16x16x32_bf16 v[4:7], v[162:165], v[202:205], v[4:7]
	v_mfma_f32_16x16x32_bf16 v[0:3], v[166:169], v[198:201], v[0:3]
	v_mfma_f32_16x16x32_bf16 v[0:3], v[170:173], v[202:205], v[0:3]
	v_mfma_f32_16x16x32_bf16 v[16:19], v[166:169], v[190:193], v[16:19]
	v_mfma_f32_16x16x32_bf16 v[16:19], v[170:173], v[194:197], v[16:19]
	v_mfma_f32_16x16x32_bf16 v[32:35], v[166:169], v[182:185], v[32:35]
	v_mfma_f32_16x16x32_bf16 v[32:35], v[170:173], v[186:189], v[32:35]
	v_mfma_f32_16x16x32_bf16 v[48:51], v[166:169], v[174:177], v[48:51]
	v_mfma_f32_16x16x32_bf16 v[48:51], v[170:173], v[178:181], v[48:51]
	s_setprio 0
	s_barrier
	ds_read_b128 v[128:131], v144
	ds_read_b128 v[132:135], v144 offset:1024
	ds_read_b128 v[136:139], v144 offset:2048
	ds_read_b128 v[140:143], v144 offset:3072
	ds_read_b128 v[146:149], v150
	ds_read_b128 v[162:165], v150 offset:1024
	ds_read_b128 v[166:169], v150 offset:2048
	ds_read_b128 v[170:173], v150 offset:3072
	ds_read_b128 v[174:177], v158 offset:32768
	ds_read_b128 v[178:181], v158 offset:33792
	ds_read_b128 v[182:185], v158 offset:34816
	ds_read_b128 v[186:189], v158 offset:35840
	ds_read_b128 v[190:193], v158 offset:36864
	ds_read_b128 v[194:197], v158 offset:37888
	ds_read_b128 v[198:201], v158 offset:38912
	ds_read_b128 v[202:205], v158 offset:39936
	s_add_u32 s12, s58, 0x4000
	s_addc_u32 s13, s59, 0
	s_mov_b32 m0, s71
	s_nop 0
	global_load_lds_dwordx4 v154, s[12:13]
	s_add_u32 s12, s58, 0x6000
	s_addc_u32 s13, s59, 0
	s_mov_b32 m0, s72
	s_nop 0
	global_load_lds_dwordx4 v154, s[12:13]
	s_waitcnt vmcnt(8)
	s_waitcnt lgkmcnt(0)
	s_barrier
	s_setprio 1
	s_waitcnt lgkmcnt(7)
	s_waitcnt lgkmcnt(0)
	v_mfma_f32_16x16x32_bf16 v[116:119], v[128:131], v[174:177], v[116:119]
	v_mfma_f32_16x16x32_bf16 v[116:119], v[132:135], v[178:181], v[116:119]
	v_mfma_f32_16x16x32_bf16 v[100:103], v[128:131], v[182:185], v[100:103]
	v_mfma_f32_16x16x32_bf16 v[100:103], v[132:135], v[186:189], v[100:103]
	v_mfma_f32_16x16x32_bf16 v[92:95], v[128:131], v[190:193], v[92:95]
	v_mfma_f32_16x16x32_bf16 v[92:95], v[132:135], v[194:197], v[92:95]
	v_mfma_f32_16x16x32_bf16 v[76:79], v[128:131], v[198:201], v[76:79]
	v_mfma_f32_16x16x32_bf16 v[76:79], v[132:135], v[202:205], v[76:79]
	v_mfma_f32_16x16x32_bf16 v[72:75], v[136:139], v[198:201], v[72:75]
	v_mfma_f32_16x16x32_bf16 v[72:75], v[140:143], v[202:205], v[72:75]
	v_mfma_f32_16x16x32_bf16 v[88:91], v[136:139], v[190:193], v[88:91]
	v_mfma_f32_16x16x32_bf16 v[88:91], v[140:143], v[194:197], v[88:91]
	v_mfma_f32_16x16x32_bf16 v[96:99], v[136:139], v[182:185], v[96:99]
	v_mfma_f32_16x16x32_bf16 v[96:99], v[140:143], v[186:189], v[96:99]
	v_mfma_f32_16x16x32_bf16 v[112:115], v[136:139], v[174:177], v[112:115]
	v_mfma_f32_16x16x32_bf16 v[112:115], v[140:143], v[178:181], v[112:115]
	s_setprio 0
	s_setprio 1
	s_waitcnt lgkmcnt(0)
	v_mfma_f32_16x16x32_bf16 v[124:127], v[146:149], v[174:177], v[124:127]
	v_mfma_f32_16x16x32_bf16 v[124:127], v[162:165], v[178:181], v[124:127]
	v_mfma_f32_16x16x32_bf16 v[108:111], v[146:149], v[182:185], v[108:111]
	v_mfma_f32_16x16x32_bf16 v[108:111], v[162:165], v[186:189], v[108:111]
	v_mfma_f32_16x16x32_bf16 v[84:87], v[146:149], v[190:193], v[84:87]
	v_mfma_f32_16x16x32_bf16 v[84:87], v[162:165], v[194:197], v[84:87]
	v_mfma_f32_16x16x32_bf16 v[68:71], v[146:149], v[198:201], v[68:71]
	v_mfma_f32_16x16x32_bf16 v[68:71], v[162:165], v[202:205], v[68:71]
	v_mfma_f32_16x16x32_bf16 v[64:67], v[166:169], v[198:201], v[64:67]
	v_mfma_f32_16x16x32_bf16 v[64:67], v[170:173], v[202:205], v[64:67]
	v_mfma_f32_16x16x32_bf16 v[80:83], v[166:169], v[190:193], v[80:83]
	v_mfma_f32_16x16x32_bf16 v[80:83], v[170:173], v[194:197], v[80:83]
	v_mfma_f32_16x16x32_bf16 v[104:107], v[166:169], v[182:185], v[104:107]
	v_mfma_f32_16x16x32_bf16 v[104:107], v[170:173], v[186:189], v[104:107]
	v_mfma_f32_16x16x32_bf16 v[120:123], v[166:169], v[174:177], v[120:123]
	v_mfma_f32_16x16x32_bf16 v[120:123], v[170:173], v[178:181], v[120:123]
	s_setprio 0
	s_barrier
	s_add_u32 s12, s64, 0xa000
	ds_read_b128 v[174:177], v158 offset:49152
	ds_read_b128 v[178:181], v158 offset:50176
	ds_read_b128 v[182:185], v158 offset:51200
	ds_read_b128 v[186:189], v158 offset:52224
	ds_read_b128 v[190:193], v158 offset:53248
	ds_read_b128 v[194:197], v158 offset:54272
	ds_read_b128 v[198:201], v158 offset:55296
	ds_read_b128 v[202:205], v158 offset:56320
	s_mov_b32 m0, s75
	s_nop 0
	global_load_lds_dwordx4 v154, s[52:53]
	s_addc_u32 s13, s65, 0
	s_mov_b32 m0, s76
	s_nop 0
	global_load_lds_dwordx4 v154, s[12:13]
	s_add_u32 s12, s64, 0xc000
	s_addc_u32 s13, s65, 0
	s_mov_b32 m0, s79
	s_nop 0
	global_load_lds_dwordx4 v154, s[12:13]
	s_add_u32 s12, s64, 0xe000
	s_addc_u32 s13, s65, 0
	s_mov_b32 m0, s80
	s_nop 0
	global_load_lds_dwordx4 v154, s[12:13]
	s_add_u32 s12, s58, 0xa000
	s_mov_b32 m0, s77
	s_nop 0
	global_load_lds_dwordx4 v154, s[60:61]
	s_addc_u32 s13, s59, 0
	s_mov_b32 m0, s78
	s_nop 0
	global_load_lds_dwordx4 v154, s[12:13]
	s_waitcnt vmcnt(8)
	s_waitcnt lgkmcnt(0)
	s_barrier
	s_setprio 1
	s_waitcnt lgkmcnt(7)
	s_waitcnt lgkmcnt(0)
	v_mfma_f32_16x16x32_bf16 v[60:63], v[128:131], v[174:177], v[60:63]
	v_mfma_f32_16x16x32_bf16 v[60:63], v[132:135], v[178:181], v[60:63]
	v_mfma_f32_16x16x32_bf16 v[44:47], v[128:131], v[182:185], v[44:47]
	v_mfma_f32_16x16x32_bf16 v[44:47], v[132:135], v[186:189], v[44:47]
	v_mfma_f32_16x16x32_bf16 v[28:31], v[128:131], v[190:193], v[28:31]
	v_mfma_f32_16x16x32_bf16 v[28:31], v[132:135], v[194:197], v[28:31]
	v_mfma_f32_16x16x32_bf16 v[12:15], v[128:131], v[198:201], v[12:15]
	v_mfma_f32_16x16x32_bf16 v[12:15], v[132:135], v[202:205], v[12:15]
	v_mfma_f32_16x16x32_bf16 v[8:11], v[136:139], v[198:201], v[8:11]
	v_mfma_f32_16x16x32_bf16 v[8:11], v[140:143], v[202:205], v[8:11]
	v_mfma_f32_16x16x32_bf16 v[24:27], v[136:139], v[190:193], v[24:27]
	v_mfma_f32_16x16x32_bf16 v[24:27], v[140:143], v[194:197], v[24:27]
	v_mfma_f32_16x16x32_bf16 v[40:43], v[136:139], v[182:185], v[40:43]
	v_mfma_f32_16x16x32_bf16 v[40:43], v[140:143], v[186:189], v[40:43]
	v_mfma_f32_16x16x32_bf16 v[56:59], v[136:139], v[174:177], v[56:59]
	v_mfma_f32_16x16x32_bf16 v[56:59], v[140:143], v[178:181], v[56:59]
	s_setprio 0
	s_setprio 1
	s_waitcnt lgkmcnt(0)
	v_mfma_f32_16x16x32_bf16 v[52:55], v[146:149], v[174:177], v[52:55]
	v_mfma_f32_16x16x32_bf16 v[52:55], v[162:165], v[178:181], v[52:55]
	v_mfma_f32_16x16x32_bf16 v[36:39], v[146:149], v[182:185], v[36:39]
	v_mfma_f32_16x16x32_bf16 v[36:39], v[162:165], v[186:189], v[36:39]
	v_mfma_f32_16x16x32_bf16 v[20:23], v[146:149], v[190:193], v[20:23]
	v_mfma_f32_16x16x32_bf16 v[20:23], v[162:165], v[194:197], v[20:23]
	v_mfma_f32_16x16x32_bf16 v[4:7], v[146:149], v[198:201], v[4:7]
	v_mfma_f32_16x16x32_bf16 v[4:7], v[162:165], v[202:205], v[4:7]
	v_mfma_f32_16x16x32_bf16 v[0:3], v[166:169], v[198:201], v[0:3]
	v_mfma_f32_16x16x32_bf16 v[0:3], v[170:173], v[202:205], v[0:3]
	v_mfma_f32_16x16x32_bf16 v[16:19], v[166:169], v[190:193], v[16:19]
	v_mfma_f32_16x16x32_bf16 v[16:19], v[170:173], v[194:197], v[16:19]
	v_mfma_f32_16x16x32_bf16 v[32:35], v[166:169], v[182:185], v[32:35]
	v_mfma_f32_16x16x32_bf16 v[32:35], v[170:173], v[186:189], v[32:35]
	v_mfma_f32_16x16x32_bf16 v[48:51], v[166:169], v[174:177], v[48:51]
	v_mfma_f32_16x16x32_bf16 v[48:51], v[170:173], v[178:181], v[48:51]
	s_setprio 0
	s_barrier
	s_add_i32 s96, s96, 2
	s_add_u32 s54, s54, 0x10000
	s_addc_u32 s55, s55, 0
	s_cmp_gt_u32 s96, 61
	s_mov_b64 s[52:53], s[2:3]
	s_cbranch_scc0 .LBB0_1505
	s_and_b64 vcc, exec, s[40:41]
	s_cbranch_vccz .LBB0_1508
	s_barrier

.LBB0_1535:
	s_add_u32 s44, s46, 0x10000
	s_waitcnt lgkmcnt(0)
	s_addc_u32 s45, s47, 0
	s_add_u32 s48, s2, 0x10000
	s_addc_u32 s49, s3, 0
	s_barrier
	s_setprio 1
	s_waitcnt lgkmcnt(7)
	s_waitcnt lgkmcnt(0)
	v_mfma_f32_16x16x32_bf16 v[32:35], v[16:19], v[72:75], 0
	v_mfma_f32_16x16x32_bf16 v[32:35], v[20:23], v[76:79], v[32:35]
	v_mfma_f32_16x16x32_bf16 v[40:43], v[16:19], v[80:83], 0
	v_mfma_f32_16x16x32_bf16 v[40:43], v[20:23], v[88:91], v[40:43]
	v_mfma_f32_16x16x32_bf16 v[48:51], v[16:19], v[92:95], 0
	v_mfma_f32_16x16x32_bf16 v[48:51], v[20:23], v[96:99], v[48:51]
	v_mfma_f32_16x16x32_bf16 v[56:59], v[16:19], v[68:71], 0
	v_mfma_f32_16x16x32_bf16 v[56:59], v[20:23], v[84:87], v[56:59]
	v_mfma_f32_16x16x32_bf16 v[60:63], v[24:27], v[68:71], 0
	v_mfma_f32_16x16x32_bf16 v[60:63], v[28:31], v[84:87], v[60:63]
	v_mfma_f32_16x16x32_bf16 v[52:55], v[24:27], v[92:95], 0
	v_mfma_f32_16x16x32_bf16 v[52:55], v[28:31], v[96:99], v[52:55]
	v_mfma_f32_16x16x32_bf16 v[44:47], v[24:27], v[80:83], 0
	v_mfma_f32_16x16x32_bf16 v[44:47], v[28:31], v[88:91], v[44:47]
	v_mfma_f32_16x16x32_bf16 v[36:39], v[24:27], v[72:75], 0
	v_mfma_f32_16x16x32_bf16 v[36:39], v[28:31], v[76:79], v[36:39]
	s_setprio 0
	s_setprio 1
	v_mfma_f32_16x16x32_bf16 v[64:67], v[0:3], v[72:75], 0
	v_mfma_f32_16x16x32_bf16 v[72:75], v[8:11], v[72:75], 0
	v_mfma_f32_16x16x32_bf16 v[64:67], v[4:7], v[76:79], v[64:67]
	v_mfma_f32_16x16x32_bf16 v[72:75], v[12:15], v[76:79], v[72:75]
	v_mfma_f32_16x16x32_bf16 v[76:79], v[0:3], v[80:83], 0
	v_mfma_f32_16x16x32_bf16 v[80:83], v[8:11], v[80:83], 0
	v_mfma_f32_16x16x32_bf16 v[76:79], v[4:7], v[88:91], v[76:79]
	v_mfma_f32_16x16x32_bf16 v[80:83], v[12:15], v[88:91], v[80:83]
	v_mfma_f32_16x16x32_bf16 v[88:91], v[0:3], v[92:95], 0
	v_mfma_f32_16x16x32_bf16 v[92:95], v[8:11], v[92:95], 0
	v_mfma_f32_16x16x32_bf16 v[88:91], v[4:7], v[96:99], v[88:91]
	v_mfma_f32_16x16x32_bf16 v[92:95], v[12:15], v[96:99], v[92:95]
	v_mfma_f32_16x16x32_bf16 v[96:99], v[0:3], v[68:71], 0
	v_mfma_f32_16x16x32_bf16 v[68:71], v[8:11], v[68:71], 0
	v_mfma_f32_16x16x32_bf16 v[128:131], v[4:7], v[84:87], v[96:99]
	v_mfma_f32_16x16x32_bf16 v[132:135], v[12:15], v[84:87], v[68:71]
	s_setprio 0
	s_barrier
	ds_read_b128 v[112:115], v140 offset:16384
	ds_read_b128 v[116:119], v140 offset:17408
	ds_read_b128 v[104:107], v140 offset:18432
	ds_read_b128 v[108:111], v140 offset:19456
	ds_read_b128 v[96:99], v140 offset:20480
	ds_read_b128 v[100:103], v140 offset:21504
	ds_read_b128 v[68:71], v140 offset:22528
	ds_read_b128 v[84:87], v140 offset:23552
	s_mov_b32 m0, s41
	s_nop 0
	global_load_lds_dwordx4 v136, s[48:49]
	s_add_u32 s48, s2, 0x12000
	s_addc_u32 s49, s3, 0
	s_mov_b32 m0, s59
	s_nop 0
	global_load_lds_dwordx4 v136, s[48:49]
	s_add_u32 s48, s2, 0x14000
	s_addc_u32 s49, s3, 0
	s_mov_b32 m0, s60
	s_nop 0
	global_load_lds_dwordx4 v136, s[48:49]
	s_add_u32 s48, s2, 0x16000
	s_addc_u32 s49, s3, 0
	s_mov_b32 m0, s61
	s_nop 0
	global_load_lds_dwordx4 v136, s[48:49]
	s_nop 0
	s_mov_b32 m0, s58
	s_nop 0
	global_load_lds_dwordx4 v136, s[44:45]
	s_add_u32 s44, s46, 0x12000
	s_addc_u32 s45, s47, 0
	s_mov_b32 m0, s62
	s_nop 0
	global_load_lds_dwordx4 v136, s[44:45]
	s_and_b64 vcc, exec, s[42:43]
	s_cbranch_vccz .LBB0_1546
	s_waitcnt vmcnt(24)
	s_cbranch_execnz .LBB0_1538

.LBB0_1539:
	ds_read_b128 v[128:131], v138
	ds_read_b128 v[132:135], v138 offset:1024
	ds_read_b128 v[144:147], v138 offset:2048
	ds_read_b128 v[148:151], v138 offset:3072
	ds_read_b128 v[152:155], v139
	ds_read_b128 v[156:159], v139 offset:1024
	ds_read_b128 v[160:163], v139 offset:2048
	ds_read_b128 v[164:167], v139 offset:3072
	s_add_u32 s2, s52, 0x10000
	s_addc_u32 s3, s53, 0
	s_cmp_eq_u32 s83, 60
	s_cselect_b32 s46, s79, s2
	s_cselect_b32 s47, s39, s3
	s_cselect_b32 s56, s80, s81
	s_cselect_b32 s57, s15, s82
	s_add_u32 s48, s46, 0x8000
	s_addc_u32 s49, s47, 0
	ds_read_b128 v[168:171], v140
	ds_read_b128 v[172:175], v140 offset:1024
	ds_read_b128 v[176:179], v140 offset:2048
	ds_read_b128 v[180:183], v140 offset:3072
	ds_read_b128 v[184:187], v140 offset:4096
	ds_read_b128 v[188:191], v140 offset:5120
	ds_read_b128 v[192:195], v140 offset:6144
	ds_read_b128 v[196:199], v140 offset:7168
	s_add_u32 s88, s52, 0xc000
	s_addc_u32 s89, s53, 0
	s_mov_b32 m0, s74
	s_nop 0
	global_load_lds_dwordx4 v136, s[88:89]
	s_add_u32 s52, s52, 0xe000
	s_addc_u32 s53, s53, 0
	s_mov_b32 m0, s75
	s_nop 0
	global_load_lds_dwordx4 v136, s[52:53]
	s_waitcnt vmcnt(8)
	s_waitcnt lgkmcnt(0)
	s_add_u32 s52, s56, 0x8000
	s_addc_u32 s53, s57, 0
	s_barrier
	s_setprio 1
	s_waitcnt lgkmcnt(7)
	s_waitcnt lgkmcnt(0)
	v_mfma_f32_16x16x32_bf16 v[120:123], v[128:131], v[168:171], v[120:123]
	v_mfma_f32_16x16x32_bf16 v[120:123], v[132:135], v[172:175], v[120:123]
	v_mfma_f32_16x16x32_bf16 v[104:107], v[128:131], v[176:179], v[104:107]
	v_mfma_f32_16x16x32_bf16 v[104:107], v[132:135], v[180:183], v[104:107]
	v_mfma_f32_16x16x32_bf16 v[84:87], v[128:131], v[184:187], v[84:87]
	v_mfma_f32_16x16x32_bf16 v[84:87], v[132:135], v[188:191], v[84:87]
	v_mfma_f32_16x16x32_bf16 v[52:55], v[128:131], v[192:195], v[52:55]
	v_mfma_f32_16x16x32_bf16 v[52:55], v[132:135], v[196:199], v[52:55]
	v_mfma_f32_16x16x32_bf16 v[36:39], v[144:147], v[192:195], v[36:39]
	v_mfma_f32_16x16x32_bf16 v[36:39], v[148:151], v[196:199], v[36:39]
	v_mfma_f32_16x16x32_bf16 v[68:71], v[144:147], v[184:187], v[68:71]
	v_mfma_f32_16x16x32_bf16 v[68:71], v[148:151], v[188:191], v[68:71]
	v_mfma_f32_16x16x32_bf16 v[96:99], v[144:147], v[176:179], v[96:99]
	v_mfma_f32_16x16x32_bf16 v[96:99], v[148:151], v[180:183], v[96:99]
	v_mfma_f32_16x16x32_bf16 v[112:115], v[144:147], v[168:171], v[112:115]
	v_mfma_f32_16x16x32_bf16 v[112:115], v[148:151], v[172:175], v[112:115]
	s_setprio 0
	s_setprio 1
	s_waitcnt lgkmcnt(0)
	v_mfma_f32_16x16x32_bf16 v[124:127], v[152:155], v[168:171], v[124:127]
	v_mfma_f32_16x16x32_bf16 v[124:127], v[156:159], v[172:175], v[124:127]
	v_mfma_f32_16x16x32_bf16 v[108:111], v[152:155], v[176:179], v[108:111]
	v_mfma_f32_16x16x32_bf16 v[108:111], v[156:159], v[180:183], v[108:111]
	v_mfma_f32_16x16x32_bf16 v[88:91], v[152:155], v[184:187], v[88:91]
	v_mfma_f32_16x16x32_bf16 v[88:91], v[156:159], v[188:191], v[88:91]
	v_mfma_f32_16x16x32_bf16 v[56:59], v[152:155], v[192:195], v[56:59]
	v_mfma_f32_16x16x32_bf16 v[56:59], v[156:159], v[196:199], v[56:59]
	v_mfma_f32_16x16x32_bf16 v[40:43], v[160:163], v[192:195], v[40:43]
	v_mfma_f32_16x16x32_bf16 v[40:43], v[164:167], v[196:199], v[40:43]
	v_mfma_f32_16x16x32_bf16 v[72:75], v[160:163], v[184:187], v[72:75]
	v_mfma_f32_16x16x32_bf16 v[72:75], v[164:167], v[188:191], v[72:75]
	v_mfma_f32_16x16x32_bf16 v[100:103], v[160:163], v[176:179], v[100:103]
	v_mfma_f32_16x16x32_bf16 v[100:103], v[164:167], v[180:183], v[100:103]
	v_mfma_f32_16x16x32_bf16 v[116:119], v[160:163], v[168:171], v[116:119]
	v_mfma_f32_16x16x32_bf16 v[116:119], v[164:167], v[172:175], v[116:119]
	s_setprio 0
	s_barrier
	s_add_u32 s88, s56, 0x2000
	ds_read_b128 v[168:171], v140 offset:16384
	ds_read_b128 v[172:175], v140 offset:17408
	ds_read_b128 v[176:179], v140 offset:18432
	ds_read_b128 v[180:183], v140 offset:19456
	ds_read_b128 v[184:187], v140 offset:20480
	ds_read_b128 v[188:191], v140 offset:21504
	ds_read_b128 v[192:195], v140 offset:22528
	ds_read_b128 v[196:199], v140 offset:23552
	s_mov_b32 m0, s41
	s_nop 0
	global_load_lds_dwordx4 v136, s[56:57]
	s_addc_u32 s89, s57, 0
	s_mov_b32 m0, s59
	s_nop 0
	global_load_lds_dwordx4 v136, s[88:89]
	s_add_u32 s88, s56, 0x4000
	s_addc_u32 s89, s57, 0
	s_mov_b32 m0, s60
	s_nop 0
	global_load_lds_dwordx4 v136, s[88:89]
	s_add_u32 s88, s56, 0x6000
	s_addc_u32 s89, s57, 0
	s_mov_b32 m0, s61
	s_nop 0
	global_load_lds_dwordx4 v136, s[88:89]
	s_add_u32 s88, s46, 0x2000
	s_mov_b32 m0, s58
	s_nop 0
	global_load_lds_dwordx4 v136, s[46:47]
	s_addc_u32 s89, s47, 0
	s_mov_b32 m0, s62
	s_nop 0
	global_load_lds_dwordx4 v136, s[88:89]
	s_waitcnt vmcnt(8)
	s_waitcnt lgkmcnt(0)
	s_barrier
	s_setprio 1
	s_waitcnt lgkmcnt(7)
	s_waitcnt lgkmcnt(0)
	v_mfma_f32_16x16x32_bf16 v[92:95], v[128:131], v[168:171], v[92:95]
	v_mfma_f32_16x16x32_bf16 v[92:95], v[132:135], v[172:175], v[92:95]
	v_mfma_f32_16x16x32_bf16 v[60:63], v[128:131], v[176:179], v[60:63]
	v_mfma_f32_16x16x32_bf16 v[60:63], v[132:135], v[180:183], v[60:63]
	v_mfma_f32_16x16x32_bf16 v[28:31], v[128:131], v[184:187], v[28:31]
	v_mfma_f32_16x16x32_bf16 v[28:31], v[132:135], v[188:191], v[28:31]
	v_mfma_f32_16x16x32_bf16 v[12:15], v[128:131], v[192:195], v[12:15]
	v_mfma_f32_16x16x32_bf16 v[12:15], v[132:135], v[196:199], v[12:15]
	v_mfma_f32_16x16x32_bf16 v[8:11], v[144:147], v[192:195], v[8:11]
	v_mfma_f32_16x16x32_bf16 v[8:11], v[148:151], v[196:199], v[8:11]
	v_mfma_f32_16x16x32_bf16 v[24:27], v[144:147], v[184:187], v[24:27]
	v_mfma_f32_16x16x32_bf16 v[24:27], v[148:151], v[188:191], v[24:27]
	v_mfma_f32_16x16x32_bf16 v[48:51], v[144:147], v[176:179], v[48:51]
	v_mfma_f32_16x16x32_bf16 v[48:51], v[148:151], v[180:183], v[48:51]
	v_mfma_f32_16x16x32_bf16 v[80:83], v[144:147], v[168:171], v[80:83]
	v_mfma_f32_16x16x32_bf16 v[80:83], v[148:151], v[172:175], v[80:83]
	s_setprio 0
	s_setprio 1
	s_waitcnt lgkmcnt(0)
	v_mfma_f32_16x16x32_bf16 v[76:79], v[152:155], v[168:171], v[76:79]
	v_mfma_f32_16x16x32_bf16 v[76:79], v[156:159], v[172:175], v[76:79]
	v_mfma_f32_16x16x32_bf16 v[44:47], v[152:155], v[176:179], v[44:47]
	v_mfma_f32_16x16x32_bf16 v[44:47], v[156:159], v[180:183], v[44:47]
	v_mfma_f32_16x16x32_bf16 v[20:23], v[152:155], v[184:187], v[20:23]
	v_mfma_f32_16x16x32_bf16 v[20:23], v[156:159], v[188:191], v[20:23]
	v_mfma_f32_16x16x32_bf16 v[4:7], v[152:155], v[192:195], v[4:7]
	v_mfma_f32_16x16x32_bf16 v[4:7], v[156:159], v[196:199], v[4:7]
	v_mfma_f32_16x16x32_bf16 v[0:3], v[160:163], v[192:195], v[0:3]
	v_mfma_f32_16x16x32_bf16 v[0:3], v[164:167], v[196:199], v[0:3]
	v_mfma_f32_16x16x32_bf16 v[16:19], v[160:163], v[184:187], v[16:19]
	v_mfma_f32_16x16x32_bf16 v[16:19], v[164:167], v[188:191], v[16:19]
	v_mfma_f32_16x16x32_bf16 v[32:35], v[160:163], v[176:179], v[32:35]
	v_mfma_f32_16x16x32_bf16 v[32:35], v[164:167], v[180:183], v[32:35]
	v_mfma_f32_16x16x32_bf16 v[64:67], v[160:163], v[168:171], v[64:67]
	v_mfma_f32_16x16x32_bf16 v[64:67], v[164:167], v[172:175], v[64:67]
	s_setprio 0
	s_barrier
	ds_read_b128 v[128:131], v141
	ds_read_b128 v[132:135], v141 offset:1024
	ds_read_b128 v[144:147], v141 offset:2048
	ds_read_b128 v[148:151], v141 offset:3072
	ds_read_b128 v[152:155], v142
	ds_read_b128 v[156:159], v142 offset:1024
	ds_read_b128 v[160:163], v142 offset:2048
	ds_read_b128 v[164:167], v142 offset:3072
	ds_read_b128 v[168:171], v140 offset:32768
	ds_read_b128 v[172:175], v140 offset:33792
	ds_read_b128 v[176:179], v140 offset:34816
	ds_read_b128 v[180:183], v140 offset:35840
	ds_read_b128 v[184:187], v140 offset:36864
	ds_read_b128 v[188:191], v140 offset:37888
	ds_read_b128 v[192:195], v140 offset:38912
	ds_read_b128 v[196:199], v140 offset:39936
	s_add_u32 s88, s46, 0x4000
	s_addc_u32 s89, s47, 0
	s_mov_b32 m0, s63
	s_nop 0
	global_load_lds_dwordx4 v136, s[88:89]
	s_add_u32 s88, s46, 0x6000
	s_addc_u32 s89, s47, 0
	s_mov_b32 m0, s64
	s_nop 0
	global_load_lds_dwordx4 v136, s[88:89]
	s_waitcnt vmcnt(8)
	s_waitcnt lgkmcnt(0)
	s_barrier
	s_setprio 1
	s_waitcnt lgkmcnt(7)
	s_waitcnt lgkmcnt(0)
	v_mfma_f32_16x16x32_bf16 v[120:123], v[128:131], v[168:171], v[120:123]
	v_mfma_f32_16x16x32_bf16 v[120:123], v[132:135], v[172:175], v[120:123]
	v_mfma_f32_16x16x32_bf16 v[104:107], v[128:131], v[176:179], v[104:107]
	v_mfma_f32_16x16x32_bf16 v[104:107], v[132:135], v[180:183], v[104:107]
	v_mfma_f32_16x16x32_bf16 v[84:87], v[128:131], v[184:187], v[84:87]
	v_mfma_f32_16x16x32_bf16 v[84:87], v[132:135], v[188:191], v[84:87]
	v_mfma_f32_16x16x32_bf16 v[52:55], v[128:131], v[192:195], v[52:55]
	v_mfma_f32_16x16x32_bf16 v[52:55], v[132:135], v[196:199], v[52:55]
	v_mfma_f32_16x16x32_bf16 v[36:39], v[144:147], v[192:195], v[36:39]
	v_mfma_f32_16x16x32_bf16 v[36:39], v[148:151], v[196:199], v[36:39]
	v_mfma_f32_16x16x32_bf16 v[68:71], v[144:147], v[184:187], v[68:71]
	v_mfma_f32_16x16x32_bf16 v[68:71], v[148:151], v[188:191], v[68:71]
	v_mfma_f32_16x16x32_bf16 v[96:99], v[144:147], v[176:179], v[96:99]
	v_mfma_f32_16x16x32_bf16 v[96:99], v[148:151], v[180:183], v[96:99]
	v_mfma_f32_16x16x32_bf16 v[112:115], v[144:147], v[168:171], v[112:115]
	v_mfma_f32_16x16x32_bf16 v[112:115], v[148:151], v[172:175], v[112:115]
	s_setprio 0
	s_setprio 1
	s_waitcnt lgkmcnt(0)
	v_mfma_f32_16x16x32_bf16 v[124:127], v[152:155], v[168:171], v[124:127]
	v_mfma_f32_16x16x32_bf16 v[124:127], v[156:159], v[172:175], v[124:127]
	v_mfma_f32_16x16x32_bf16 v[108:111], v[152:155], v[176:179], v[108:111]
	v_mfma_f32_16x16x32_bf16 v[108:111], v[156:159], v[180:183], v[108:111]
	v_mfma_f32_16x16x32_bf16 v[88:91], v[152:155], v[184:187], v[88:91]
	v_mfma_f32_16x16x32_bf16 v[88:91], v[156:159], v[188:191], v[88:91]
	v_mfma_f32_16x16x32_bf16 v[56:59], v[152:155], v[192:195], v[56:59]
	v_mfma_f32_16x16x32_bf16 v[56:59], v[156:159], v[196:199], v[56:59]
	v_mfma_f32_16x16x32_bf16 v[40:43], v[160:163], v[192:195], v[40:43]
	v_mfma_f32_16x16x32_bf16 v[40:43], v[164:167], v[196:199], v[40:43]
	v_mfma_f32_16x16x32_bf16 v[72:75], v[160:163], v[184:187], v[72:75]
	v_mfma_f32_16x16x32_bf16 v[72:75], v[164:167], v[188:191], v[72:75]
	v_mfma_f32_16x16x32_bf16 v[100:103], v[160:163], v[176:179], v[100:103]
	v_mfma_f32_16x16x32_bf16 v[100:103], v[164:167], v[180:183], v[100:103]
	v_mfma_f32_16x16x32_bf16 v[116:119], v[160:163], v[168:171], v[116:119]
	v_mfma_f32_16x16x32_bf16 v[116:119], v[164:167], v[172:175], v[116:119]
	s_setprio 0
	s_barrier
	ds_read_b128 v[168:171], v140 offset:49152
	ds_read_b128 v[172:175], v140 offset:50176
	ds_read_b128 v[176:179], v140 offset:51200
	ds_read_b128 v[180:183], v140 offset:52224
	ds_read_b128 v[184:187], v140 offset:53248
	ds_read_b128 v[188:191], v140 offset:54272
	ds_read_b128 v[192:195], v140 offset:55296
	ds_read_b128 v[196:199], v140 offset:56320
	s_mov_b32 m0, s68
	s_nop 0
	global_load_lds_dwordx4 v136, s[52:53]
	s_add_u32 s52, s56, 0xa000
	s_addc_u32 s53, s57, 0
	s_mov_b32 m0, s69
	s_nop 0
	global_load_lds_dwordx4 v136, s[52:53]
	s_add_u32 s52, s56, 0xc000
	s_addc_u32 s53, s57, 0
	s_mov_b32 m0, s72
	s_nop 0
	global_load_lds_dwordx4 v136, s[52:53]
	s_add_u32 s52, s56, 0xe000
	s_addc_u32 s53, s57, 0
	s_mov_b32 m0, s73
	s_nop 0
	global_load_lds_dwordx4 v136, s[52:53]
	s_add_u32 s46, s46, 0xa000
	s_mov_b32 m0, s70
	s_nop 0
	global_load_lds_dwordx4 v136, s[48:49]
	s_addc_u32 s47, s47, 0
	s_mov_b32 m0, s71
	s_nop 0
	global_load_lds_dwordx4 v136, s[46:47]
	s_waitcnt vmcnt(8)
	s_waitcnt lgkmcnt(0)
	s_barrier
	s_setprio 1
	s_waitcnt lgkmcnt(7)
	s_waitcnt lgkmcnt(0)
	v_mfma_f32_16x16x32_bf16 v[92:95], v[128:131], v[168:171], v[92:95]
	v_mfma_f32_16x16x32_bf16 v[92:95], v[132:135], v[172:175], v[92:95]
	v_mfma_f32_16x16x32_bf16 v[60:63], v[128:131], v[176:179], v[60:63]
	v_mfma_f32_16x16x32_bf16 v[60:63], v[132:135], v[180:183], v[60:63]
	v_mfma_f32_16x16x32_bf16 v[28:31], v[128:131], v[184:187], v[28:31]
	v_mfma_f32_16x16x32_bf16 v[28:31], v[132:135], v[188:191], v[28:31]
	v_mfma_f32_16x16x32_bf16 v[12:15], v[128:131], v[192:195], v[12:15]
	v_mfma_f32_16x16x32_bf16 v[12:15], v[132:135], v[196:199], v[12:15]
	v_mfma_f32_16x16x32_bf16 v[8:11], v[144:147], v[192:195], v[8:11]
	v_mfma_f32_16x16x32_bf16 v[8:11], v[148:151], v[196:199], v[8:11]
	v_mfma_f32_16x16x32_bf16 v[24:27], v[144:147], v[184:187], v[24:27]
	v_mfma_f32_16x16x32_bf16 v[24:27], v[148:151], v[188:191], v[24:27]
	v_mfma_f32_16x16x32_bf16 v[48:51], v[144:147], v[176:179], v[48:51]
	v_mfma_f32_16x16x32_bf16 v[48:51], v[148:151], v[180:183], v[48:51]
	v_mfma_f32_16x16x32_bf16 v[80:83], v[144:147], v[168:171], v[80:83]
	v_mfma_f32_16x16x32_bf16 v[80:83], v[148:151], v[172:175], v[80:83]
	s_setprio 0
	s_setprio 1
	s_waitcnt lgkmcnt(0)
	v_mfma_f32_16x16x32_bf16 v[76:79], v[152:155], v[168:171], v[76:79]
	v_mfma_f32_16x16x32_bf16 v[76:79], v[156:159], v[172:175], v[76:79]
	v_mfma_f32_16x16x32_bf16 v[44:47], v[152:155], v[176:179], v[44:47]
	v_mfma_f32_16x16x32_bf16 v[44:47], v[156:159], v[180:183], v[44:47]
	v_mfma_f32_16x16x32_bf16 v[20:23], v[152:155], v[184:187], v[20:23]
	v_mfma_f32_16x16x32_bf16 v[20:23], v[156:159], v[188:191], v[20:23]
	v_mfma_f32_16x16x32_bf16 v[4:7], v[152:155], v[192:195], v[4:7]
	v_mfma_f32_16x16x32_bf16 v[4:7], v[156:159], v[196:199], v[4:7]
	v_mfma_f32_16x16x32_bf16 v[0:3], v[160:163], v[192:195], v[0:3]
	v_mfma_f32_16x16x32_bf16 v[0:3], v[164:167], v[196:199], v[0:3]
	v_mfma_f32_16x16x32_bf16 v[16:19], v[160:163], v[184:187], v[16:19]
	v_mfma_f32_16x16x32_bf16 v[16:19], v[164:167], v[188:191], v[16:19]
	v_mfma_f32_16x16x32_bf16 v[32:35], v[160:163], v[176:179], v[32:35]
	v_mfma_f32_16x16x32_bf16 v[32:35], v[164:167], v[180:183], v[32:35]
	v_mfma_f32_16x16x32_bf16 v[64:67], v[160:163], v[168:171], v[64:67]
	v_mfma_f32_16x16x32_bf16 v[64:67], v[164:167], v[172:175], v[64:67]
	s_setprio 0
	s_barrier
	s_add_i32 s83, s83, 2
	s_add_u32 s81, s81, 0x10000
	s_addc_u32 s82, s82, 0
	s_cmp_gt_u32 s83, 61
	s_mov_b64 s[52:53], s[2:3]
	s_cbranch_scc0 .LBB0_1539
	s_and_b64 vcc, exec, s[8:9]
	s_cbranch_vccz .LBB0_1542
	s_barrier

.LBB0_1675:
	ds_read_b128 v[48:51], v214
	ds_read_b128 v[64:67], v214 offset:1024
	ds_read_b128 v[80:83], v214 offset:2048
	ds_read_b128 v[92:95], v214 offset:3072
	ds_read_b128 v[104:107], v215
	ds_read_b128 v[116:119], v215 offset:1024
	ds_read_b128 v[140:143], v215 offset:2048
	ds_read_b128 v[144:147], v215 offset:3072
	s_cmp_eq_u32 s93, 4
	s_cselect_b32 s2, s89, s54
	s_cselect_b32 s3, s43, s55
	s_cselect_b32 s60, s90, s91
	s_cselect_b32 s61, s41, s92
	s_add_u32 s58, s2, 0x8000
	s_addc_u32 s59, s3, 0
	ds_read_b128 v[156:159], v216
	ds_read_b128 v[168:171], v216 offset:1024
	ds_read_b128 v[172:175], v216 offset:2048
	ds_read_b128 v[176:179], v216 offset:3072
	ds_read_b128 v[180:183], v216 offset:4096
	ds_read_b128 v[184:187], v216 offset:5120
	ds_read_b128 v[188:191], v216 offset:6144
	ds_read_b128 v[194:197], v216 offset:7168
	s_add_u32 s52, s54, 0xffffc000
	s_addc_u32 s53, s55, -1
	s_mov_b32 m0, s77
	s_nop 0
	global_load_lds_dwordx4 v212, s[52:53]
	s_add_u32 s52, s54, 0xffffe000
	s_addc_u32 s53, s55, -1
	s_mov_b32 m0, s81
	s_nop 0
	global_load_lds_dwordx4 v212, s[52:53]
	s_waitcnt vmcnt(8)
	s_waitcnt lgkmcnt(0)
	s_add_u32 s52, s60, 0x8000
	s_addc_u32 s53, s61, 0
	s_barrier
	s_setprio 1
	s_waitcnt lgkmcnt(7)
	v_mfma_f32_16x16x32_bf16 v[164:167], v[48:51], v[156:159], v[164:167]
	v_mfma_f32_16x16x32_bf16 v[160:163], v[80:83], v[156:159], v[160:163]
	s_waitcnt lgkmcnt(5)
	v_mfma_f32_16x16x32_bf16 v[136:139], v[48:51], v[172:175], v[136:139]
	v_mfma_f32_16x16x32_bf16 v[130:133], v[80:83], v[172:175], v[132:135]
	s_waitcnt lgkmcnt(3)
	v_mfma_f32_16x16x32_bf16 v[112:115], v[48:51], v[180:183], v[112:115]
	v_mfma_f32_16x16x32_bf16 v[108:111], v[80:83], v[180:183], v[108:111]
	s_waitcnt lgkmcnt(1)
	v_mfma_f32_16x16x32_bf16 v[88:91], v[48:51], v[188:191], v[88:91]
	v_mfma_f32_16x16x32_bf16 v[84:87], v[80:83], v[188:191], v[84:87]
	v_mfma_f32_16x16x32_bf16 v[164:167], v[64:67], v[168:171], v[164:167]
	v_mfma_f32_16x16x32_bf16 v[160:163], v[92:95], v[168:171], v[160:163]
	v_mfma_f32_16x16x32_bf16 v[136:139], v[64:67], v[176:179], v[136:139]
	v_mfma_f32_16x16x32_bf16 v[130:133], v[92:95], v[176:179], v[130:133]
	v_mfma_f32_16x16x32_bf16 v[112:115], v[64:67], v[184:187], v[112:115]
	v_mfma_f32_16x16x32_bf16 v[108:111], v[92:95], v[184:187], v[108:111]
	s_waitcnt lgkmcnt(0)
	v_mfma_f32_16x16x32_bf16 v[88:91], v[64:67], v[194:197], v[88:91]
	v_mfma_f32_16x16x32_bf16 v[84:87], v[92:95], v[194:197], v[84:87]
	s_setprio 0
	s_setprio 1
	s_waitcnt lgkmcnt(0)
	v_mfma_f32_16x16x32_bf16 v[152:155], v[104:107], v[156:159], v[152:155]
	v_mfma_f32_16x16x32_bf16 v[152:155], v[116:119], v[168:171], v[152:155]
	v_mfma_f32_16x16x32_bf16 v[124:127], v[104:107], v[172:175], v[124:127]
	v_mfma_f32_16x16x32_bf16 v[124:127], v[116:119], v[176:179], v[124:127]
	v_mfma_f32_16x16x32_bf16 v[100:103], v[104:107], v[180:183], v[100:103]
	v_mfma_f32_16x16x32_bf16 v[100:103], v[116:119], v[184:187], v[100:103]
	v_mfma_f32_16x16x32_bf16 v[76:79], v[104:107], v[188:191], v[76:79]
	v_mfma_f32_16x16x32_bf16 v[76:79], v[116:119], v[194:197], v[76:79]
	v_mfma_f32_16x16x32_bf16 v[72:75], v[140:143], v[188:191], v[72:75]
	v_mfma_f32_16x16x32_bf16 v[72:75], v[144:147], v[194:197], v[72:75]
	v_mfma_f32_16x16x32_bf16 v[96:99], v[140:143], v[180:183], v[96:99]
	v_mfma_f32_16x16x32_bf16 v[96:99], v[144:147], v[184:187], v[96:99]
	v_mfma_f32_16x16x32_bf16 v[120:123], v[140:143], v[172:175], v[120:123]
	v_mfma_f32_16x16x32_bf16 v[120:123], v[144:147], v[176:179], v[120:123]
	v_mfma_f32_16x16x32_bf16 v[148:151], v[140:143], v[156:159], v[148:151]
	v_mfma_f32_16x16x32_bf16 v[148:151], v[144:147], v[168:171], v[148:151]
	s_setprio 0
	s_barrier
	s_add_u32 s96, s60, 0x2000
	ds_read_b128 v[156:159], v216 offset:16384
	ds_read_b128 v[168:171], v216 offset:17408
	ds_read_b128 v[172:175], v216 offset:18432
	ds_read_b128 v[176:179], v216 offset:19456
	ds_read_b128 v[180:183], v216 offset:20480
	ds_read_b128 v[184:187], v216 offset:21504
	ds_read_b128 v[188:191], v216 offset:22528
	ds_read_b128 v[194:197], v216 offset:23552
	s_mov_b32 m0, s49
	s_nop 0
	global_load_lds_dwordx4 v212, s[60:61]
	s_addc_u32 s97, s61, 0
	s_mov_b32 m0, s57
	s_nop 0
	global_load_lds_dwordx4 v212, s[96:97]
	s_add_u32 s96, s60, 0x4000
	s_addc_u32 s97, s61, 0
	s_mov_b32 m0, s63
	s_nop 0
	global_load_lds_dwordx4 v212, s[96:97]
	s_add_u32 s96, s60, 0x6000
	s_addc_u32 s97, s61, 0
	s_mov_b32 m0, s64
	s_nop 0
	global_load_lds_dwordx4 v212, s[96:97]
	s_add_u32 s96, s2, 0x2000
	s_mov_b32 m0, s62
	s_nop 0
	global_load_lds_dwordx4 v212, s[2:3]
	s_addc_u32 s97, s3, 0
	s_mov_b32 m0, s65
	s_nop 0
	global_load_lds_dwordx4 v212, s[96:97]
	s_waitcnt vmcnt(8)
	s_waitcnt lgkmcnt(0)
	s_barrier
	s_setprio 1
	s_waitcnt lgkmcnt(7)
	s_waitcnt lgkmcnt(0)
	v_mfma_f32_16x16x32_bf16 v[68:71], v[48:51], v[156:159], v[68:71]
	v_mfma_f32_16x16x32_bf16 v[68:71], v[64:67], v[168:171], v[68:71]
	v_mfma_f32_16x16x32_bf16 v[44:47], v[48:51], v[172:175], v[44:47]
	v_mfma_f32_16x16x32_bf16 v[44:47], v[64:67], v[176:179], v[44:47]
	v_mfma_f32_16x16x32_bf16 v[28:31], v[48:51], v[180:183], v[28:31]
	v_mfma_f32_16x16x32_bf16 v[28:31], v[64:67], v[184:187], v[28:31]
	v_mfma_f32_16x16x32_bf16 v[12:15], v[48:51], v[188:191], v[12:15]
	v_mfma_f32_16x16x32_bf16 v[12:15], v[64:67], v[194:197], v[12:15]
	v_mfma_f32_16x16x32_bf16 v[8:11], v[80:83], v[188:191], v[8:11]
	v_mfma_f32_16x16x32_bf16 v[8:11], v[92:95], v[194:197], v[8:11]
	v_mfma_f32_16x16x32_bf16 v[24:27], v[80:83], v[180:183], v[24:27]
	v_mfma_f32_16x16x32_bf16 v[24:27], v[92:95], v[184:187], v[24:27]
	v_mfma_f32_16x16x32_bf16 v[40:43], v[80:83], v[172:175], v[40:43]
	v_mfma_f32_16x16x32_bf16 v[40:43], v[92:95], v[176:179], v[40:43]
	v_mfma_f32_16x16x32_bf16 v[60:63], v[80:83], v[156:159], v[60:63]
	v_mfma_f32_16x16x32_bf16 v[60:63], v[92:95], v[168:171], v[60:63]
	s_setprio 0
	s_setprio 1
	v_mfma_f32_16x16x32_bf16 v[52:55], v[140:143], v[156:159], v[52:55]
	v_mfma_f32_16x16x32_bf16 v[36:39], v[104:107], v[172:175], v[36:39]
	v_mfma_f32_16x16x32_bf16 v[32:35], v[140:143], v[172:175], v[32:35]
	v_mfma_f32_16x16x32_bf16 v[20:23], v[104:107], v[180:183], v[20:23]
	v_mfma_f32_16x16x32_bf16 v[16:19], v[140:143], v[180:183], v[16:19]
	v_mfma_f32_16x16x32_bf16 v[4:7], v[104:107], v[188:191], v[4:7]
	v_mfma_f32_16x16x32_bf16 v[0:3], v[140:143], v[188:191], v[0:3]
	v_mfma_f32_16x16x32_bf16 v[48:51], v[104:107], v[156:159], v[56:59]
	v_mfma_f32_16x16x32_bf16 v[52:55], v[144:147], v[168:171], v[52:55]
	v_mfma_f32_16x16x32_bf16 v[36:39], v[116:119], v[176:179], v[36:39]
	v_mfma_f32_16x16x32_bf16 v[32:35], v[144:147], v[176:179], v[32:35]
	v_mfma_f32_16x16x32_bf16 v[20:23], v[116:119], v[184:187], v[20:23]
	v_mfma_f32_16x16x32_bf16 v[16:19], v[144:147], v[184:187], v[16:19]
	v_mfma_f32_16x16x32_bf16 v[4:7], v[116:119], v[194:197], v[4:7]
	v_mfma_f32_16x16x32_bf16 v[0:3], v[144:147], v[194:197], v[0:3]
	v_mfma_f32_16x16x32_bf16 v[48:51], v[116:119], v[168:171], v[48:51]
	s_setprio 0
	s_barrier
	ds_read_b128 v[56:59], v128
	ds_read_b128 v[64:67], v128 offset:1024
	ds_read_b128 v[80:83], v128 offset:2048
	ds_read_b128 v[92:95], v128 offset:3072
	ds_read_b128 v[104:107], v129
	ds_read_b128 v[116:119], v129 offset:1024
	ds_read_b128 v[140:143], v129 offset:2048
	ds_read_b128 v[144:147], v129 offset:3072
	ds_read_b128 v[156:159], v216 offset:32768
	ds_read_b128 v[168:171], v216 offset:33792
	ds_read_b128 v[172:175], v216 offset:34816
	ds_read_b128 v[176:179], v216 offset:35840
	ds_read_b128 v[180:183], v216 offset:36864
	ds_read_b128 v[184:187], v216 offset:37888
	ds_read_b128 v[188:191], v216 offset:38912
	ds_read_b128 v[194:197], v216 offset:39936
	s_add_u32 s96, s2, 0x4000
	s_addc_u32 s97, s3, 0
	s_mov_b32 m0, s66
	s_nop 0
	global_load_lds_dwordx4 v212, s[96:97]
	s_add_u32 s96, s2, 0x6000
	s_addc_u32 s97, s3, 0
	s_mov_b32 m0, s67
	s_nop 0
	global_load_lds_dwordx4 v212, s[96:97]
	s_waitcnt vmcnt(8)
	s_waitcnt lgkmcnt(0)
	s_barrier
	s_setprio 1
	s_waitcnt lgkmcnt(7)
	v_mfma_f32_16x16x32_bf16 v[164:167], v[56:59], v[156:159], v[164:167]
	v_mfma_f32_16x16x32_bf16 v[160:163], v[80:83], v[156:159], v[160:163]
	s_waitcnt lgkmcnt(5)
	v_mfma_f32_16x16x32_bf16 v[134:137], v[56:59], v[172:175], v[136:139]
	v_mfma_f32_16x16x32_bf16 v[130:133], v[80:83], v[172:175], v[130:133]
	s_waitcnt lgkmcnt(3)
	v_mfma_f32_16x16x32_bf16 v[112:115], v[56:59], v[180:183], v[112:115]
	v_mfma_f32_16x16x32_bf16 v[108:111], v[80:83], v[180:183], v[108:111]
	s_waitcnt lgkmcnt(1)
	v_mfma_f32_16x16x32_bf16 v[88:91], v[56:59], v[188:191], v[88:91]
	v_mfma_f32_16x16x32_bf16 v[84:87], v[80:83], v[188:191], v[84:87]
	v_mfma_f32_16x16x32_bf16 v[164:167], v[64:67], v[168:171], v[164:167]
	v_mfma_f32_16x16x32_bf16 v[160:163], v[92:95], v[168:171], v[160:163]
	v_mfma_f32_16x16x32_bf16 v[136:139], v[64:67], v[176:179], v[134:137]
	v_mfma_f32_16x16x32_bf16 v[132:135], v[92:95], v[176:179], v[130:133]
	v_mfma_f32_16x16x32_bf16 v[112:115], v[64:67], v[184:187], v[112:115]
	v_mfma_f32_16x16x32_bf16 v[108:111], v[92:95], v[184:187], v[108:111]
	s_waitcnt lgkmcnt(0)
	v_mfma_f32_16x16x32_bf16 v[88:91], v[64:67], v[194:197], v[88:91]
	v_mfma_f32_16x16x32_bf16 v[84:87], v[92:95], v[194:197], v[84:87]
	s_setprio 0
	s_setprio 1
	s_waitcnt lgkmcnt(0)
	v_mfma_f32_16x16x32_bf16 v[152:155], v[104:107], v[156:159], v[152:155]
	v_mfma_f32_16x16x32_bf16 v[152:155], v[116:119], v[168:171], v[152:155]
	v_mfma_f32_16x16x32_bf16 v[124:127], v[104:107], v[172:175], v[124:127]
	v_mfma_f32_16x16x32_bf16 v[124:127], v[116:119], v[176:179], v[124:127]
	v_mfma_f32_16x16x32_bf16 v[100:103], v[104:107], v[180:183], v[100:103]
	v_mfma_f32_16x16x32_bf16 v[100:103], v[116:119], v[184:187], v[100:103]
	v_mfma_f32_16x16x32_bf16 v[76:79], v[104:107], v[188:191], v[76:79]
	v_mfma_f32_16x16x32_bf16 v[76:79], v[116:119], v[194:197], v[76:79]
	v_mfma_f32_16x16x32_bf16 v[72:75], v[140:143], v[188:191], v[72:75]
	v_mfma_f32_16x16x32_bf16 v[72:75], v[144:147], v[194:197], v[72:75]
	v_mfma_f32_16x16x32_bf16 v[96:99], v[140:143], v[180:183], v[96:99]
	v_mfma_f32_16x16x32_bf16 v[96:99], v[144:147], v[184:187], v[96:99]
	v_mfma_f32_16x16x32_bf16 v[120:123], v[140:143], v[172:175], v[120:123]
	v_mfma_f32_16x16x32_bf16 v[120:123], v[144:147], v[176:179], v[120:123]
	v_mfma_f32_16x16x32_bf16 v[148:151], v[140:143], v[156:159], v[148:151]
	v_mfma_f32_16x16x32_bf16 v[148:151], v[144:147], v[168:171], v[148:151]
	s_setprio 0
	s_barrier
	ds_read_b128 v[156:159], v216 offset:49152
	ds_read_b128 v[168:171], v216 offset:50176
	ds_read_b128 v[172:175], v216 offset:51200
	ds_read_b128 v[176:179], v216 offset:52224
	ds_read_b128 v[180:183], v216 offset:53248
	ds_read_b128 v[184:187], v216 offset:54272
	ds_read_b128 v[188:191], v216 offset:55296
	ds_read_b128 v[194:197], v216 offset:56320
	s_mov_b32 m0, s71
	s_nop 0
	global_load_lds_dwordx4 v212, s[52:53]
	s_add_u32 s52, s60, 0xa000
	s_addc_u32 s53, s61, 0
	s_mov_b32 m0, s72
	s_nop 0
	global_load_lds_dwordx4 v212, s[52:53]
	s_add_u32 s52, s60, 0xc000
	s_addc_u32 s53, s61, 0
	s_mov_b32 m0, s75
	s_nop 0
	global_load_lds_dwordx4 v212, s[52:53]
	s_add_u32 s52, s60, 0xe000
	s_addc_u32 s53, s61, 0
	s_mov_b32 m0, s76
	s_nop 0
	global_load_lds_dwordx4 v212, s[52:53]
	s_add_u32 s2, s2, 0xa000
	s_mov_b32 m0, s73
	s_nop 0
	global_load_lds_dwordx4 v212, s[58:59]
	s_addc_u32 s3, s3, 0
	s_mov_b32 m0, s74
	s_nop 0
	global_load_lds_dwordx4 v212, s[2:3]
	s_waitcnt vmcnt(8)
	s_waitcnt lgkmcnt(0)
	s_barrier
	s_setprio 1
	s_waitcnt lgkmcnt(7)
	s_waitcnt lgkmcnt(0)
	v_mfma_f32_16x16x32_bf16 v[68:71], v[56:59], v[156:159], v[68:71]
	v_mfma_f32_16x16x32_bf16 v[68:71], v[64:67], v[168:171], v[68:71]
	v_mfma_f32_16x16x32_bf16 v[44:47], v[56:59], v[172:175], v[44:47]
	v_mfma_f32_16x16x32_bf16 v[44:47], v[64:67], v[176:179], v[44:47]
	v_mfma_f32_16x16x32_bf16 v[28:31], v[56:59], v[180:183], v[28:31]
	v_mfma_f32_16x16x32_bf16 v[28:31], v[64:67], v[184:187], v[28:31]
	v_mfma_f32_16x16x32_bf16 v[12:15], v[56:59], v[188:191], v[12:15]
	v_mfma_f32_16x16x32_bf16 v[12:15], v[64:67], v[194:197], v[12:15]
	v_mfma_f32_16x16x32_bf16 v[8:11], v[80:83], v[188:191], v[8:11]
	v_mfma_f32_16x16x32_bf16 v[8:11], v[92:95], v[194:197], v[8:11]
	v_mfma_f32_16x16x32_bf16 v[24:27], v[80:83], v[180:183], v[24:27]
	v_mfma_f32_16x16x32_bf16 v[24:27], v[92:95], v[184:187], v[24:27]
	v_mfma_f32_16x16x32_bf16 v[40:43], v[80:83], v[172:175], v[40:43]
	v_mfma_f32_16x16x32_bf16 v[40:43], v[92:95], v[176:179], v[40:43]
	v_mfma_f32_16x16x32_bf16 v[60:63], v[80:83], v[156:159], v[60:63]
	v_mfma_f32_16x16x32_bf16 v[60:63], v[92:95], v[168:171], v[60:63]
	s_setprio 0
	s_setprio 1
	v_mfma_f32_16x16x32_bf16 v[48:51], v[104:107], v[156:159], v[48:51]
	v_mfma_f32_16x16x32_bf16 v[56:59], v[116:119], v[168:171], v[48:51]
	v_mfma_f32_16x16x32_bf16 v[48:51], v[140:143], v[156:159], v[52:55]
	v_mfma_f32_16x16x32_bf16 v[36:39], v[104:107], v[172:175], v[36:39]
	v_mfma_f32_16x16x32_bf16 v[32:35], v[140:143], v[172:175], v[32:35]
	v_mfma_f32_16x16x32_bf16 v[20:23], v[104:107], v[180:183], v[20:23]
	v_mfma_f32_16x16x32_bf16 v[16:19], v[140:143], v[180:183], v[16:19]
	v_mfma_f32_16x16x32_bf16 v[4:7], v[104:107], v[188:191], v[4:7]
	v_mfma_f32_16x16x32_bf16 v[0:3], v[140:143], v[188:191], v[0:3]
	v_mfma_f32_16x16x32_bf16 v[52:55], v[144:147], v[168:171], v[48:51]
	v_mfma_f32_16x16x32_bf16 v[36:39], v[116:119], v[176:179], v[36:39]
	v_mfma_f32_16x16x32_bf16 v[32:35], v[144:147], v[176:179], v[32:35]
	v_mfma_f32_16x16x32_bf16 v[20:23], v[116:119], v[184:187], v[20:23]
	v_mfma_f32_16x16x32_bf16 v[16:19], v[144:147], v[184:187], v[16:19]
	v_mfma_f32_16x16x32_bf16 v[4:7], v[116:119], v[194:197], v[4:7]
	v_mfma_f32_16x16x32_bf16 v[0:3], v[144:147], v[194:197], v[0:3]
	s_setprio 0
	s_barrier
	s_add_i32 s93, s93, 2
	s_add_u32 s54, s54, 0x10000
	s_addc_u32 s55, s55, 0
	s_add_u32 s91, s91, 0x10000
	s_addc_u32 s92, s92, 0
	s_cmp_gt_u32 s93, 5
	s_cbranch_scc0 .LBB0_1675
	s_and_b64 vcc, exec, s[14:15]
	s_cbranch_vccz .LBB0_1678
	s_barrier

.LBB0_1953:
	ds_read_b128 v[134:137], v128
	ds_read_b128 v[138:141], v128 offset:1024
	ds_read_b128 v[142:145], v128 offset:2048
	ds_read_b128 v[146:149], v128 offset:3072
	ds_read_b128 v[150:153], v129
	ds_read_b128 v[154:157], v129 offset:1024
	ds_read_b128 v[158:161], v129 offset:2048
	ds_read_b128 v[162:165], v129 offset:3072
	s_add_u32 s2, s28, 0x10000
	s_addc_u32 s3, s29, 0
	s_cmp_eq_u32 s77, 8
	s_cselect_b32 s38, s26, s2
	s_cselect_b32 s39, s27, s3
	s_cselect_b32 s42, s23, s75
	s_cselect_b32 s43, s25, s76
	s_add_u32 s40, s38, 0x8000
	s_addc_u32 s41, s39, 0
	ds_read_b128 v[166:169], v130
	ds_read_b128 v[170:173], v130 offset:1024
	ds_read_b128 v[174:177], v130 offset:2048
	ds_read_b128 v[178:181], v130 offset:3072
	ds_read_b128 v[182:185], v130 offset:4096
	ds_read_b128 v[192:195], v130 offset:5120
	ds_read_b128 v[196:199], v130 offset:6144
	ds_read_b128 v[200:203], v130 offset:7168
	s_add_u32 s78, s28, 0xc000
	s_addc_u32 s79, s29, 0
	s_mov_b32 m0, s63
	s_nop 0
	global_load_lds_dwordx4 v210, s[78:79]
	s_add_u32 s28, s28, 0xe000
	s_addc_u32 s29, s29, 0
	s_mov_b32 m0, s66
	s_nop 0
	global_load_lds_dwordx4 v210, s[28:29]
	s_waitcnt vmcnt(8)
	s_waitcnt lgkmcnt(0)
	s_barrier
	s_setprio 1
	s_waitcnt lgkmcnt(7)
	s_waitcnt lgkmcnt(0)
	v_mfma_f32_16x16x32_bf16 v[124:127], v[134:137], v[166:169], v[124:127]
	v_mfma_f32_16x16x32_bf16 v[124:127], v[138:141], v[170:173], v[124:127]
	v_mfma_f32_16x16x32_bf16 v[108:111], v[134:137], v[174:177], v[108:111]
	v_mfma_f32_16x16x32_bf16 v[108:111], v[138:141], v[178:181], v[108:111]
	v_mfma_f32_16x16x32_bf16 v[92:95], v[134:137], v[182:185], v[92:95]
	v_mfma_f32_16x16x32_bf16 v[92:95], v[138:141], v[192:195], v[92:95]
	v_mfma_f32_16x16x32_bf16 v[76:79], v[134:137], v[196:199], v[76:79]
	v_mfma_f32_16x16x32_bf16 v[76:79], v[138:141], v[200:203], v[76:79]
	v_mfma_f32_16x16x32_bf16 v[72:75], v[142:145], v[196:199], v[72:75]
	v_mfma_f32_16x16x32_bf16 v[72:75], v[146:149], v[200:203], v[72:75]
	v_mfma_f32_16x16x32_bf16 v[88:91], v[142:145], v[182:185], v[88:91]
	v_mfma_f32_16x16x32_bf16 v[88:91], v[146:149], v[192:195], v[88:91]
	v_mfma_f32_16x16x32_bf16 v[104:107], v[142:145], v[174:177], v[104:107]
	v_mfma_f32_16x16x32_bf16 v[104:107], v[146:149], v[178:181], v[104:107]
	v_mfma_f32_16x16x32_bf16 v[120:123], v[142:145], v[166:169], v[120:123]
	v_mfma_f32_16x16x32_bf16 v[120:123], v[146:149], v[170:173], v[120:123]
	s_setprio 0
	s_setprio 1
	s_waitcnt lgkmcnt(0)
	v_mfma_f32_16x16x32_bf16 v[116:119], v[150:153], v[166:169], v[116:119]
	v_mfma_f32_16x16x32_bf16 v[116:119], v[154:157], v[170:173], v[116:119]
	v_mfma_f32_16x16x32_bf16 v[100:103], v[150:153], v[174:177], v[100:103]
	v_mfma_f32_16x16x32_bf16 v[100:103], v[154:157], v[178:181], v[100:103]
	v_mfma_f32_16x16x32_bf16 v[84:87], v[150:153], v[182:185], v[84:87]
	v_mfma_f32_16x16x32_bf16 v[84:87], v[154:157], v[192:195], v[84:87]
	v_mfma_f32_16x16x32_bf16 v[68:71], v[150:153], v[196:199], v[68:71]
	v_mfma_f32_16x16x32_bf16 v[68:71], v[154:157], v[200:203], v[68:71]
	v_mfma_f32_16x16x32_bf16 v[64:67], v[158:161], v[196:199], v[64:67]
	v_mfma_f32_16x16x32_bf16 v[64:67], v[162:165], v[200:203], v[64:67]
	v_mfma_f32_16x16x32_bf16 v[80:83], v[158:161], v[182:185], v[80:83]
	v_mfma_f32_16x16x32_bf16 v[80:83], v[162:165], v[192:195], v[80:83]
	v_mfma_f32_16x16x32_bf16 v[96:99], v[158:161], v[174:177], v[96:99]
	v_mfma_f32_16x16x32_bf16 v[96:99], v[162:165], v[178:181], v[96:99]
	v_mfma_f32_16x16x32_bf16 v[112:115], v[158:161], v[166:169], v[112:115]
	v_mfma_f32_16x16x32_bf16 v[112:115], v[162:165], v[170:173], v[112:115]
	s_setprio 0
	s_barrier
	s_add_u32 s28, s42, 0x2000
	ds_read_b128 v[166:169], v130 offset:16384
	ds_read_b128 v[170:173], v130 offset:17408
	ds_read_b128 v[174:177], v130 offset:18432
	ds_read_b128 v[178:181], v130 offset:19456
	ds_read_b128 v[182:185], v130 offset:20480
	ds_read_b128 v[192:195], v130 offset:21504
	ds_read_b128 v[196:199], v130 offset:22528
	ds_read_b128 v[200:203], v130 offset:23552
	s_mov_b32 m0, s46
	s_nop 0
	global_load_lds_dwordx4 v210, s[42:43]
	s_addc_u32 s29, s43, 0
	s_mov_b32 m0, s47
	s_nop 0
	global_load_lds_dwordx4 v210, s[28:29]
	s_add_u32 s28, s42, 0x4000
	s_addc_u32 s29, s43, 0
	s_mov_b32 m0, s48
	s_nop 0
	global_load_lds_dwordx4 v210, s[28:29]
	s_add_u32 s28, s42, 0x6000
	s_addc_u32 s29, s43, 0
	s_mov_b32 m0, s49
	s_nop 0
	global_load_lds_dwordx4 v210, s[28:29]
	s_add_u32 s28, s38, 0x2000
	s_mov_b32 m0, s45
	s_nop 0
	global_load_lds_dwordx4 v210, s[38:39]
	s_addc_u32 s29, s39, 0
	s_mov_b32 m0, s50
	s_nop 0
	global_load_lds_dwordx4 v210, s[28:29]
	s_waitcnt vmcnt(8)
	s_waitcnt lgkmcnt(0)
	s_barrier
	s_setprio 1
	s_waitcnt lgkmcnt(7)
	s_waitcnt lgkmcnt(0)
	v_mfma_f32_16x16x32_bf16 v[60:63], v[134:137], v[166:169], v[60:63]
	v_mfma_f32_16x16x32_bf16 v[60:63], v[138:141], v[170:173], v[60:63]
	v_mfma_f32_16x16x32_bf16 v[44:47], v[134:137], v[174:177], v[44:47]
	v_mfma_f32_16x16x32_bf16 v[44:47], v[138:141], v[178:181], v[44:47]
	v_mfma_f32_16x16x32_bf16 v[28:31], v[134:137], v[182:185], v[28:31]
	v_mfma_f32_16x16x32_bf16 v[28:31], v[138:141], v[192:195], v[28:31]
	v_mfma_f32_16x16x32_bf16 v[12:15], v[134:137], v[196:199], v[12:15]
	v_mfma_f32_16x16x32_bf16 v[12:15], v[138:141], v[200:203], v[12:15]
	v_mfma_f32_16x16x32_bf16 v[8:11], v[142:145], v[196:199], v[8:11]
	v_mfma_f32_16x16x32_bf16 v[8:11], v[146:149], v[200:203], v[8:11]
	v_mfma_f32_16x16x32_bf16 v[24:27], v[142:145], v[182:185], v[24:27]
	v_mfma_f32_16x16x32_bf16 v[24:27], v[146:149], v[192:195], v[24:27]
	v_mfma_f32_16x16x32_bf16 v[40:43], v[142:145], v[174:177], v[40:43]
	v_mfma_f32_16x16x32_bf16 v[40:43], v[146:149], v[178:181], v[40:43]
	v_mfma_f32_16x16x32_bf16 v[56:59], v[142:145], v[166:169], v[56:59]
	v_mfma_f32_16x16x32_bf16 v[56:59], v[146:149], v[170:173], v[56:59]
	s_setprio 0
	s_setprio 1
	s_waitcnt lgkmcnt(0)
	v_mfma_f32_16x16x32_bf16 v[52:55], v[150:153], v[166:169], v[52:55]
	v_mfma_f32_16x16x32_bf16 v[52:55], v[154:157], v[170:173], v[52:55]
	v_mfma_f32_16x16x32_bf16 v[36:39], v[150:153], v[174:177], v[36:39]
	v_mfma_f32_16x16x32_bf16 v[36:39], v[154:157], v[178:181], v[36:39]
	v_mfma_f32_16x16x32_bf16 v[20:23], v[150:153], v[182:185], v[20:23]
	v_mfma_f32_16x16x32_bf16 v[20:23], v[154:157], v[192:195], v[20:23]
	v_mfma_f32_16x16x32_bf16 v[4:7], v[150:153], v[196:199], v[4:7]
	v_mfma_f32_16x16x32_bf16 v[4:7], v[154:157], v[200:203], v[4:7]
	v_mfma_f32_16x16x32_bf16 v[0:3], v[158:161], v[196:199], v[0:3]
	v_mfma_f32_16x16x32_bf16 v[0:3], v[162:165], v[200:203], v[0:3]
	v_mfma_f32_16x16x32_bf16 v[16:19], v[158:161], v[182:185], v[16:19]
	v_mfma_f32_16x16x32_bf16 v[16:19], v[162:165], v[192:195], v[16:19]
	v_mfma_f32_16x16x32_bf16 v[32:35], v[158:161], v[174:177], v[32:35]
	v_mfma_f32_16x16x32_bf16 v[32:35], v[162:165], v[178:181], v[32:35]
	v_mfma_f32_16x16x32_bf16 v[48:51], v[158:161], v[166:169], v[48:51]
	v_mfma_f32_16x16x32_bf16 v[48:51], v[162:165], v[170:173], v[48:51]
	s_setprio 0
	s_barrier
	ds_read_b128 v[134:137], v131
	ds_read_b128 v[138:141], v131 offset:1024
	ds_read_b128 v[142:145], v131 offset:2048
	ds_read_b128 v[146:149], v131 offset:3072
	ds_read_b128 v[150:153], v132
	ds_read_b128 v[154:157], v132 offset:1024
	ds_read_b128 v[158:161], v132 offset:2048
	ds_read_b128 v[162:165], v132 offset:3072
	ds_read_b128 v[166:169], v130 offset:32768
	ds_read_b128 v[170:173], v130 offset:33792
	ds_read_b128 v[174:177], v130 offset:34816
	ds_read_b128 v[178:181], v130 offset:35840
	ds_read_b128 v[182:185], v130 offset:36864
	ds_read_b128 v[192:195], v130 offset:37888
	ds_read_b128 v[196:199], v130 offset:38912
	ds_read_b128 v[200:203], v130 offset:39936
	s_add_u32 s28, s38, 0x4000
	s_addc_u32 s29, s39, 0
	s_mov_b32 m0, s51
	s_nop 0
	global_load_lds_dwordx4 v210, s[28:29]
	s_add_u32 s28, s38, 0x6000
	s_addc_u32 s29, s39, 0
	s_mov_b32 m0, s52
	s_nop 0
	global_load_lds_dwordx4 v210, s[28:29]
	s_waitcnt vmcnt(8)
	s_waitcnt lgkmcnt(0)
	s_barrier
	s_setprio 1
	s_waitcnt lgkmcnt(7)
	s_waitcnt lgkmcnt(0)
	v_mfma_f32_16x16x32_bf16 v[124:127], v[134:137], v[166:169], v[124:127]
	v_mfma_f32_16x16x32_bf16 v[124:127], v[138:141], v[170:173], v[124:127]
	v_mfma_f32_16x16x32_bf16 v[108:111], v[134:137], v[174:177], v[108:111]
	v_mfma_f32_16x16x32_bf16 v[108:111], v[138:141], v[178:181], v[108:111]
	v_mfma_f32_16x16x32_bf16 v[92:95], v[134:137], v[182:185], v[92:95]
	v_mfma_f32_16x16x32_bf16 v[92:95], v[138:141], v[192:195], v[92:95]
	v_mfma_f32_16x16x32_bf16 v[76:79], v[134:137], v[196:199], v[76:79]
	v_mfma_f32_16x16x32_bf16 v[76:79], v[138:141], v[200:203], v[76:79]
	v_mfma_f32_16x16x32_bf16 v[72:75], v[142:145], v[196:199], v[72:75]
	v_mfma_f32_16x16x32_bf16 v[72:75], v[146:149], v[200:203], v[72:75]
	v_mfma_f32_16x16x32_bf16 v[88:91], v[142:145], v[182:185], v[88:91]
	v_mfma_f32_16x16x32_bf16 v[88:91], v[146:149], v[192:195], v[88:91]
	v_mfma_f32_16x16x32_bf16 v[104:107], v[142:145], v[174:177], v[104:107]
	v_mfma_f32_16x16x32_bf16 v[104:107], v[146:149], v[178:181], v[104:107]
	v_mfma_f32_16x16x32_bf16 v[120:123], v[142:145], v[166:169], v[120:123]
	v_mfma_f32_16x16x32_bf16 v[120:123], v[146:149], v[170:173], v[120:123]
	s_setprio 0
	s_setprio 1
	s_waitcnt lgkmcnt(0)
	v_mfma_f32_16x16x32_bf16 v[116:119], v[150:153], v[166:169], v[116:119]
	v_mfma_f32_16x16x32_bf16 v[116:119], v[154:157], v[170:173], v[116:119]
	v_mfma_f32_16x16x32_bf16 v[100:103], v[150:153], v[174:177], v[100:103]
	v_mfma_f32_16x16x32_bf16 v[100:103], v[154:157], v[178:181], v[100:103]
	v_mfma_f32_16x16x32_bf16 v[84:87], v[150:153], v[182:185], v[84:87]
	v_mfma_f32_16x16x32_bf16 v[84:87], v[154:157], v[192:195], v[84:87]
	v_mfma_f32_16x16x32_bf16 v[68:71], v[150:153], v[196:199], v[68:71]
	v_mfma_f32_16x16x32_bf16 v[68:71], v[154:157], v[200:203], v[68:71]
	v_mfma_f32_16x16x32_bf16 v[64:67], v[158:161], v[196:199], v[64:67]
	v_mfma_f32_16x16x32_bf16 v[64:67], v[162:165], v[200:203], v[64:67]
	v_mfma_f32_16x16x32_bf16 v[80:83], v[158:161], v[182:185], v[80:83]
	v_mfma_f32_16x16x32_bf16 v[80:83], v[162:165], v[192:195], v[80:83]
	v_mfma_f32_16x16x32_bf16 v[96:99], v[158:161], v[174:177], v[96:99]
	v_mfma_f32_16x16x32_bf16 v[96:99], v[162:165], v[178:181], v[96:99]
	v_mfma_f32_16x16x32_bf16 v[112:115], v[158:161], v[166:169], v[112:115]
	v_mfma_f32_16x16x32_bf16 v[112:115], v[162:165], v[170:173], v[112:115]
	s_setprio 0
	s_barrier
	s_add_u32 s28, s42, 0x8000
	s_addc_u32 s29, s43, 0
	ds_read_b128 v[166:169], v130 offset:49152
	ds_read_b128 v[170:173], v130 offset:50176
	ds_read_b128 v[174:177], v130 offset:51200
	ds_read_b128 v[178:181], v130 offset:52224
	ds_read_b128 v[182:185], v130 offset:53248
	ds_read_b128 v[192:195], v130 offset:54272
	ds_read_b128 v[196:199], v130 offset:55296
	ds_read_b128 v[200:203], v130 offset:56320
	s_mov_b32 m0, s53
	s_nop 0
	global_load_lds_dwordx4 v210, s[28:29]
	s_add_u32 s28, s42, 0xa000
	s_addc_u32 s29, s43, 0
	s_mov_b32 m0, s54
	s_nop 0
	global_load_lds_dwordx4 v210, s[28:29]
	s_add_u32 s28, s42, 0xc000
	s_addc_u32 s29, s43, 0
	s_mov_b32 m0, s57
	s_nop 0
	global_load_lds_dwordx4 v210, s[28:29]
	s_add_u32 s28, s42, 0xe000
	s_addc_u32 s29, s43, 0
	s_mov_b32 m0, s58
	s_nop 0
	global_load_lds_dwordx4 v210, s[28:29]
	s_add_u32 s28, s38, 0xa000
	s_mov_b32 m0, s55
	s_nop 0
	global_load_lds_dwordx4 v210, s[40:41]
	s_addc_u32 s29, s39, 0
	s_mov_b32 m0, s56
	s_nop 0
	global_load_lds_dwordx4 v210, s[28:29]
	s_waitcnt vmcnt(8)
	s_waitcnt lgkmcnt(0)
	s_barrier
	s_setprio 1
	s_waitcnt lgkmcnt(7)
	s_waitcnt lgkmcnt(0)
	v_mfma_f32_16x16x32_bf16 v[60:63], v[134:137], v[166:169], v[60:63]
	v_mfma_f32_16x16x32_bf16 v[60:63], v[138:141], v[170:173], v[60:63]
	v_mfma_f32_16x16x32_bf16 v[44:47], v[134:137], v[174:177], v[44:47]
	v_mfma_f32_16x16x32_bf16 v[44:47], v[138:141], v[178:181], v[44:47]
	v_mfma_f32_16x16x32_bf16 v[28:31], v[134:137], v[182:185], v[28:31]
	v_mfma_f32_16x16x32_bf16 v[28:31], v[138:141], v[192:195], v[28:31]
	v_mfma_f32_16x16x32_bf16 v[12:15], v[134:137], v[196:199], v[12:15]
	v_mfma_f32_16x16x32_bf16 v[12:15], v[138:141], v[200:203], v[12:15]
	v_mfma_f32_16x16x32_bf16 v[8:11], v[142:145], v[196:199], v[8:11]
	v_mfma_f32_16x16x32_bf16 v[8:11], v[146:149], v[200:203], v[8:11]
	v_mfma_f32_16x16x32_bf16 v[24:27], v[142:145], v[182:185], v[24:27]
	v_mfma_f32_16x16x32_bf16 v[24:27], v[146:149], v[192:195], v[24:27]
	v_mfma_f32_16x16x32_bf16 v[40:43], v[142:145], v[174:177], v[40:43]
	v_mfma_f32_16x16x32_bf16 v[40:43], v[146:149], v[178:181], v[40:43]
	v_mfma_f32_16x16x32_bf16 v[56:59], v[142:145], v[166:169], v[56:59]
	v_mfma_f32_16x16x32_bf16 v[56:59], v[146:149], v[170:173], v[56:59]
	s_setprio 0
	s_setprio 1
	s_waitcnt lgkmcnt(0)
	v_mfma_f32_16x16x32_bf16 v[52:55], v[150:153], v[166:169], v[52:55]
	v_mfma_f32_16x16x32_bf16 v[52:55], v[154:157], v[170:173], v[52:55]
	v_mfma_f32_16x16x32_bf16 v[36:39], v[150:153], v[174:177], v[36:39]
	v_mfma_f32_16x16x32_bf16 v[36:39], v[154:157], v[178:181], v[36:39]
	v_mfma_f32_16x16x32_bf16 v[20:23], v[150:153], v[182:185], v[20:23]
	v_mfma_f32_16x16x32_bf16 v[20:23], v[154:157], v[192:195], v[20:23]
	v_mfma_f32_16x16x32_bf16 v[4:7], v[150:153], v[196:199], v[4:7]
	v_mfma_f32_16x16x32_bf16 v[4:7], v[154:157], v[200:203], v[4:7]
	v_mfma_f32_16x16x32_bf16 v[0:3], v[158:161], v[196:199], v[0:3]
	v_mfma_f32_16x16x32_bf16 v[0:3], v[162:165], v[200:203], v[0:3]
	v_mfma_f32_16x16x32_bf16 v[16:19], v[158:161], v[182:185], v[16:19]
	v_mfma_f32_16x16x32_bf16 v[16:19], v[162:165], v[192:195], v[16:19]
	v_mfma_f32_16x16x32_bf16 v[32:35], v[158:161], v[174:177], v[32:35]
	v_mfma_f32_16x16x32_bf16 v[32:35], v[162:165], v[178:181], v[32:35]
	v_mfma_f32_16x16x32_bf16 v[48:51], v[158:161], v[166:169], v[48:51]
	v_mfma_f32_16x16x32_bf16 v[48:51], v[162:165], v[170:173], v[48:51]
	s_setprio 0
	s_barrier
	s_add_i32 s77, s77, 2
	s_add_u32 s75, s75, 0x10000
	s_addc_u32 s76, s76, 0
	s_cmp_gt_u32 s77, 9
	s_mov_b64 s[28:29], s[2:3]
	s_cbranch_scc0 .LBB0_1953
	v_mbcnt_lo_u32_b32 v128, -1, 0
	v_mbcnt_hi_u32_b32 v128, -1, v128
	s_add_u32 s19, s69, s19
	v_lshlrev_b32_e32 v128, 4, v128
	v_add_u32_e32 v129, s60, v128
	v_add_u32_e32 v128, s62, v128
	s_addc_u32 s17, s70, s17
	s_mov_b32 s23, -2
	v_add_u32_e32 v128, 0, v128
	v_add_u32_e32 v129, 0, v129
